# wave reductions fully off LDS: xor-32/xor-16 butterfly steps via v_permlane32_swap / v_permlane16_swap, xor 8..1 via DPP adds
# baseline (speedup 1.0000x reference)
.LBB0_15:
	v_ashrrev_i32_e32 v1, 31, v0
	v_lshlrev_b64 v[2:3], 12, v[0:1]
	v_lshl_add_u64 v[2:3], v[70:71], 0, v[2:3]
	global_load_dwordx2 v[64:65], v[2:3], off offset:512 nt
	global_load_dwordx2 v[66:67], v[2:3], off offset:1024 nt
	global_load_dwordx2 v[86:87], v[2:3], off offset:1536 nt
	v_add_u32_e32 v181, s55, v0
	global_load_dwordx2 v[88:89], v[2:3], off offset:2048 nt
	global_load_dwordx2 v[90:91], v[2:3], off offset:2560 nt
	v_cmp_gt_i32_e32 vcc, s76, v181
	s_waitcnt vmcnt(4)
	v_lshlrev_b32_e32 v162, 16, v64
	v_cndmask_b32_e32 v4, v0, v181, vcc
	v_ashrrev_i32_e32 v5, 31, v4
	v_lshlrev_b64 v[6:7], 12, v[4:5]
	v_lshlrev_b64 v[0:1], 13, v[0:1]
	v_lshl_add_u64 v[8:9], v[70:71], 0, v[6:7]
	v_lshl_add_u64 v[84:85], v[80:81], 0, v[0:1]
	global_load_dwordx2 v[92:93], v[8:9], off offset:512 nt
	global_load_dwordx2 v[94:95], v[8:9], off offset:1024 nt
	global_load_dwordx2 v[96:97], v[8:9], off offset:1536 nt
	global_load_dwordx2 v[100:101], v[8:9], off offset:2048 nt
	global_load_dwordx2 v[102:103], v[8:9], off offset:2560 nt
	global_load_dwordx2 v[170:171], v[2:3], off nt
	global_load_dwordx2 v[176:177], v[8:9], off nt
	global_load_dwordx4 v[56:59], v[84:85], off nt
	global_load_dwordx4 v[48:51], v[84:85], off offset:1024 nt
	global_load_dwordx4 v[40:43], v[84:85], off offset:2048 nt
	global_load_dwordx4 v[32:35], v[84:85], off offset:3072 nt
	global_load_dwordx2 v[110:111], v[2:3], off offset:3072 nt
	global_load_dwordx2 v[178:179], v[8:9], off offset:3072 nt
	global_load_dwordx2 v[182:183], v[2:3], off offset:3584 nt
	v_lshlrev_b64 v[0:1], 13, v[4:5]
	v_add_co_u32_e64 v4, s[10:11], s29, v84
	v_lshl_add_u64 v[82:83], v[80:81], 0, v[0:1]
	s_nop 0
	v_addc_co_u32_e64 v5, s[10:11], 0, v85, s[10:11]
	v_add_co_u32_e64 v0, s[10:11], s29, v82
	global_load_dwordx4 v[28:31], v[4:5], off nt
	global_load_dwordx4 v[20:23], v[4:5], off offset:1024 nt
	global_load_dwordx4 v[12:15], v[4:5], off offset:2048 nt
	s_nop 0
	global_load_dwordx4 v[4:7], v[4:5], off offset:3072 nt
	s_nop 0
	global_load_dwordx4 v[60:63], v[82:83], off nt
	global_load_dwordx4 v[52:55], v[82:83], off offset:1024 nt
	global_load_dwordx4 v[44:47], v[82:83], off offset:2048 nt
	global_load_dwordx4 v[36:39], v[82:83], off offset:3072 nt
	v_addc_co_u32_e64 v1, s[10:11], 0, v83, s[10:11]
	global_load_dwordx2 v[192:193], v[8:9], off offset:3584 nt
	global_load_dwordx4 v[24:27], v[0:1], off nt
	global_load_dwordx4 v[16:19], v[0:1], off offset:1024 nt
	s_nop 0
	global_load_dwordx4 v[8:11], v[0:1], off offset:2048 nt
	s_nop 0
	global_load_dwordx4 v[0:3], v[0:1], off offset:3072 nt
	s_waitcnt vmcnt(28)
	v_and_b32_e32 v99, 0xffff0000, v88
	s_waitcnt vmcnt(27)
	v_lshlrev_b32_e32 v98, 16, v90
	v_and_b32_e32 v117, 0xffff0000, v90
	v_mov_b32_e32 v116, v99
	v_and_b32_e32 v167, 0xffff0000, v64
	v_lshlrev_b32_e32 v164, 16, v65
	v_and_b32_e32 v169, 0xffff0000, v65
	v_lshlrev_b32_e32 v104, 16, v88
	v_lshlrev_b32_e32 v122, 16, v91
	v_mov_b32_e32 v105, v98
	v_pk_mul_f32 v[64:65], v[116:117], v[116:117]
	v_lshlrev_b32_e32 v108, 16, v89
	v_and_b32_e32 v125, 0xffff0000, v89
	v_pk_fma_f32 v[64:65], v[104:105], v[104:105], v[64:65]
	v_mov_b32_e32 v109, v122
	v_and_b32_e32 v133, 0xffff0000, v91
	v_pk_fma_f32 v[64:65], v[108:109], v[108:109], v[64:65]
	v_mov_b32_e32 v132, v125
	v_pk_fma_f32 v[194:195], v[132:133], v[132:133], v[64:65]
	v_lshlrev_b32_e32 v134, 16, v86
	v_and_b32_e32 v139, 0xffff0000, v86
	v_lshlrev_b32_e32 v136, 16, v87
	v_and_b32_e32 v141, 0xffff0000, v87
	v_lshlrev_b32_e32 v150, 16, v66
	v_and_b32_e32 v155, 0xffff0000, v66
	v_lshlrev_b32_e32 v152, 16, v67
	v_and_b32_e32 v157, 0xffff0000, v67
	v_mov_b32_e32 v175, v162
	v_mov_b32_e32 v173, v164
	v_mov_b32_e32 v161, v150
	v_mov_b32_e32 v159, v152
	v_mov_b32_e32 v145, v134
	v_mov_b32_e32 v143, v136
	s_waitcnt vmcnt(26)
	v_lshlrev_b32_e32 v174, 16, v92
	s_waitcnt vmcnt(25)
	v_lshlrev_b32_e32 v160, 16, v94
	s_waitcnt vmcnt(24)
	v_lshlrev_b32_e32 v144, 16, v96
	s_waitcnt vmcnt(23)
	v_and_b32_e32 v121, 0xffff0000, v100
	s_waitcnt vmcnt(22)
	v_lshlrev_b32_e32 v116, 16, v102
	v_and_b32_e32 v129, 0xffff0000, v102
	v_mov_b32_e32 v128, v121
	v_lshlrev_b32_e32 v114, 16, v100
	v_lshlrev_b32_e32 v120, 16, v103
	v_mov_b32_e32 v115, v116
	v_pk_mul_f32 v[64:65], v[128:129], v[128:129]
	v_lshlrev_b32_e32 v112, 16, v101
	v_and_b32_e32 v123, 0xffff0000, v101
	v_pk_fma_f32 v[64:65], v[114:115], v[114:115], v[64:65]
	v_mov_b32_e32 v113, v120
	s_waitcnt vmcnt(15)
	v_and_b32_e32 v119, 0xffff0000, v110
	v_and_b32_e32 v147, 0xffff0000, v96
	v_and_b32_e32 v131, 0xffff0000, v103
	v_pk_fma_f32 v[64:65], v[112:113], v[112:113], v[64:65]
	v_mov_b32_e32 v130, v123
	s_waitcnt vmcnt(13)
	v_lshlrev_b32_e32 v96, 16, v182
	v_and_b32_e32 v87, 0xffff0000, v182
	v_mov_b32_e32 v86, v119
	v_and_b32_e32 v135, 0xffff0000, v94
	v_pk_fma_f32 v[196:197], v[130:131], v[130:131], v[64:65]
	v_lshlrev_b32_e32 v106, 16, v110
	v_lshlrev_b32_e32 v94, 16, v183
	v_mov_b32_e32 v107, v96
	v_pk_mul_f32 v[64:65], v[86:87], v[86:87]
	v_lshlrev_b32_e32 v158, 16, v95
	v_and_b32_e32 v137, 0xffff0000, v95
	v_lshlrev_b32_e32 v110, 16, v111
	v_and_b32_e32 v127, 0xffff0000, v111
	v_and_b32_e32 v95, 0xffff0000, v178
	v_pk_fma_f32 v[64:65], v[106:107], v[106:107], v[64:65]
	v_mov_b32_e32 v111, v94
	v_and_b32_e32 v89, 0xffff0000, v183
	v_pk_fma_f32 v[64:65], v[110:111], v[110:111], v[64:65]
	v_mov_b32_e32 v88, v127
	s_waitcnt vmcnt(4)
	v_lshlrev_b32_e32 v86, 16, v192
	v_and_b32_e32 v91, 0xffff0000, v192
	v_mov_b32_e32 v90, v95
	v_lshlrev_b32_e32 v100, 16, v178
	v_pk_fma_f32 v[182:183], v[88:89], v[88:89], v[64:65]
	v_lshlrev_b32_e32 v88, 16, v193
	v_mov_b32_e32 v101, v86
	v_pk_mul_f32 v[64:65], v[90:91], v[90:91]
	v_lshlrev_b32_e32 v142, 16, v97
	v_and_b32_e32 v149, 0xffff0000, v97
	v_lshlrev_b32_e32 v102, 16, v179
	v_and_b32_e32 v97, 0xffff0000, v179
	v_pk_fma_f32 v[64:65], v[100:101], v[100:101], v[64:65]
	v_mov_b32_e32 v103, v88
	v_and_b32_e32 v151, 0xffff0000, v92
	v_lshlrev_b32_e32 v172, 16, v93
	v_and_b32_e32 v153, 0xffff0000, v93
	v_and_b32_e32 v93, 0xffff0000, v193
	v_pk_fma_f32 v[64:65], v[102:103], v[102:103], v[64:65]
	v_mov_b32_e32 v92, v97
	v_pk_fma_f32 v[192:193], v[92:93], v[92:93], v[64:65]
	v_and_b32_e32 v101, 0xffff0000, v176
	v_and_b32_e32 v199, 0xffff0000, v170
	v_lshlrev_b32_e32 v198, 16, v170
	v_mov_b32_e32 v166, v151
	v_mov_b32_e32 v206, v101
	v_mov_b32_e32 v207, v199
	v_lshlrev_b32_e32 v178, 16, v176
	v_lshlrev_b32_e32 v200, 16, v171
	v_and_b32_e32 v201, 0xffff0000, v171
	v_pk_mul_f32 v[170:171], v[166:167], v[166:167]
	v_mov_b32_e32 v154, v135
	v_mov_b32_e32 v179, v198
	v_pk_mul_f32 v[206:207], v[206:207], v[206:207]
	v_lshlrev_b32_e32 v176, 16, v177
	v_and_b32_e32 v103, 0xffff0000, v177
	v_pk_fma_f32 v[170:171], v[174:175], v[174:175], v[170:171]
	v_pk_mul_f32 v[202:203], v[154:155], v[154:155]
	v_mov_b32_e32 v138, v147
	v_pk_fma_f32 v[206:207], v[178:179], v[178:179], v[206:207]
	v_mov_b32_e32 v177, v200
	v_pk_fma_f32 v[170:171], v[172:173], v[172:173], v[170:171]
	v_mov_b32_e32 v168, v153
	v_pk_fma_f32 v[202:203], v[160:161], v[160:161], v[202:203]
	v_pk_mul_f32 v[204:205], v[138:139], v[138:139]
	v_mov_b32_e32 v208, v103
	v_mov_b32_e32 v209, v201
	v_pk_fma_f32 v[206:207], v[176:177], v[176:177], v[206:207]
	v_pk_fma_f32 v[170:171], v[168:169], v[168:169], v[170:171]
	v_pk_fma_f32 v[202:203], v[158:159], v[158:159], v[202:203]
	v_mov_b32_e32 v156, v137
	v_pk_fma_f32 v[204:205], v[144:145], v[144:145], v[204:205]
	v_pk_fma_f32 v[206:207], v[208:209], v[208:209], v[206:207]
	v_pk_fma_f32 v[202:203], v[156:157], v[156:157], v[202:203]
	v_pk_fma_f32 v[204:205], v[142:143], v[142:143], v[204:205]
	v_mov_b32_e32 v140, v149
	v_pk_add_f32 v[170:171], v[206:207], v[170:171]
	v_pk_fma_f32 v[204:205], v[140:141], v[140:141], v[204:205]
	v_pk_add_f32 v[170:171], v[170:171], v[202:203]
	v_mov_b32_e32 v202, v196
	v_pk_add_f32 v[170:171], v[170:171], v[204:205]
	v_mov_b32_e32 v203, v194
	v_pk_add_f32 v[170:171], v[170:171], v[202:203]
	v_mov_b32_e32 v194, v197
	v_pk_add_f32 v[170:171], v[170:171], v[194:195]
	v_mov_b32_e32 v194, v192
	v_mov_b32_e32 v195, v182
	v_pk_add_f32 v[170:171], v[170:171], v[194:195]
	v_mov_b32_e32 v182, v193
	v_pk_add_f32 v[170:171], v[170:171], v[182:183]
	v_mov_b32_e32 v182, v170
	v_mov_b32_e32 v183, v171
	s_nop 1
	v_permlane32_swap_b32_e32 v182, v170
	v_permlane32_swap_b32_e32 v183, v171
	v_add_f32_e32 v170, v170, v182
	v_add_f32_e32 v171, v171, v183
	v_mov_b32_e32 v182, v170
	v_mov_b32_e32 v183, v171
	s_nop 1
	v_permlane16_swap_b32_e32 v182, v170
	v_permlane16_swap_b32_e32 v183, v171
	v_add_f32_e32 v170, v170, v182
	v_add_f32_e32 v171, v171, v183
	s_nop 1
	v_add_f32_dpp v170, v170, v170 row_mirror row_mask:0xf bank_mask:0xf
	v_add_f32_dpp v171, v171, v171 row_mirror row_mask:0xf bank_mask:0xf
	s_nop 1
	v_add_f32_dpp v170, v170, v170 row_half_mirror row_mask:0xf bank_mask:0xf
	v_add_f32_dpp v171, v171, v171 row_half_mirror row_mask:0xf bank_mask:0xf
	s_nop 1
	v_add_f32_dpp v170, v170, v170 quad_perm:[2,3,0,1] row_mask:0xf bank_mask:0xf
	v_add_f32_dpp v171, v171, v171 quad_perm:[2,3,0,1] row_mask:0xf bank_mask:0xf
	s_nop 1
	v_add_f32_dpp v170, v170, v170 quad_perm:[1,0,3,2] row_mask:0xf bank_mask:0xf
	v_add_f32_dpp v171, v171, v171 quad_perm:[1,0,3,2] row_mask:0xf bank_mask:0xf
	s_nop 0
	v_pk_fma_f32 v[170:171], v[170:171], s[34:35], v[188:189] op_sel_hi:[1,0,0]
	s_nop 0
	v_mul_f32_e32 v90, 0x4b800000, v170
	v_cmp_gt_f32_e64 s[10:11], s80, v170
	v_mul_f32_e32 v92, 0x4b800000, v171
	v_cmp_gt_f32_e64 s[12:13], s80, v171
	v_cndmask_b32_e64 v90, v170, v90, s[10:11]
	v_rsq_f32_e32 v90, v90
	v_cndmask_b32_e64 v92, v171, v92, s[12:13]
	v_rsq_f32_e32 v92, v92
	v_mul_f32_e32 v105, 0x45800000, v90
	v_cndmask_b32_e64 v90, v90, v105, s[10:11]
	v_mul_f32_e32 v105, 0x45800000, v92
	v_cndmask_b32_e64 v170, v92, v105, s[12:13]
	v_pk_mul_f32 v[182:183], v[170:171], v[198:199] op_sel_hi:[0,1]
	s_waitcnt vmcnt(0)
	v_pk_fma_f32 v[56:57], v[210:211], v[182:183], v[56:57]
	v_pk_mul_f32 v[182:183], v[170:171], v[200:201] op_sel_hi:[0,1]
	v_pk_fma_f32 v[58:59], v[212:213], v[182:183], v[58:59]
	global_store_dwordx4 v[84:85], v[56:59], off nt
	s_and_saveexec_b64 s[4:5], vcc
	s_cbranch_execz .LBB0_17
	v_mov_b32_e32 v177, v103
	v_mov_b32_e32 v179, v101
	v_pk_mul_f32 v[56:57], v[90:91], v[178:179] op_sel_hi:[0,1]
	v_pk_mul_f32 v[58:59], v[90:91], v[176:177] op_sel_hi:[0,1]
	v_pk_fma_f32 v[56:57], v[210:211], v[56:57], v[60:61]
	v_pk_fma_f32 v[58:59], v[212:213], v[58:59], v[62:63]
	global_store_dwordx4 v[82:83], v[56:59], off nt

.LBB0_132:
	v_add_co_u32_e32 v12, vcc, 0x8000000, v100
	v_add_u32_e32 v0, s55, v132
	s_nop 0
	v_addc_co_u32_e32 v13, vcc, 0, v101, vcc
	v_cmp_gt_i32_e64 s[10:11], s76, v0
	global_load_dwordx2 v[32:33], v[12:13], off offset:512 nt
	global_load_dwordx2 v[38:39], v[12:13], off offset:1024 nt
	global_load_dwordx2 v[108:109], v[12:13], off offset:1536 nt
	v_cndmask_b32_e64 v16, v132, v0, s[10:11]
	global_load_dwordx2 v[110:111], v[12:13], off offset:2048 nt
	v_ashrrev_i32_e32 v17, 31, v16
	v_lshlrev_b64 v[106:107], 12, v[16:17]
	v_lshl_add_u64 v[44:45], v[76:77], 0, v[106:107]
	global_load_dwordx2 v[112:113], v[44:45], off offset:512 nt
	global_load_dwordx2 v[114:115], v[44:45], off offset:1024 nt
	global_load_dwordx2 v[116:117], v[44:45], off offset:1536 nt
	global_load_dwordx2 v[118:119], v[44:45], off offset:2048 nt
	global_load_dwordx2 v[122:123], v[12:13], off offset:2560 nt
	global_load_dwordx2 v[124:125], v[44:45], off offset:2560 nt
	global_load_dwordx2 v[14:15], v[12:13], off nt
	global_load_dwordx2 v[120:121], v[44:45], off nt
	v_lshl_add_u64 v[18:19], v[104:105], 0, v[186:187]
	global_load_dwordx4 v[4:7], v[18:19], off nt
	global_load_dwordx4 v[0:3], v[18:19], off offset:1024 nt
	global_load_dwordx4 v[8:11], v[18:19], off offset:2048 nt
	global_load_dwordx4 v[20:23], v[18:19], off offset:3072 nt
	global_load_dwordx2 v[128:129], v[12:13], off offset:3072 nt
	v_add_co_u32_e32 v18, vcc, s29, v18
	s_waitcnt vmcnt(16)
	v_lshlrev_b32_e32 v198, 16, v32
	v_addc_co_u32_e32 v19, vcc, 0, v19, vcc
	global_load_dwordx2 v[136:137], v[44:45], off offset:3072 nt
	global_load_dwordx4 v[28:31], v[18:19], off nt
	global_load_dwordx4 v[40:43], v[18:19], off offset:1024 nt
	global_load_dwordx2 v[138:139], v[12:13], off offset:3584 nt
	global_load_dwordx4 v[48:51], v[18:19], off offset:2048 nt
	global_load_dwordx4 v[56:59], v[18:19], off offset:3072 nt
	v_lshlrev_b64 v[12:13], 13, v[16:17]
	v_lshl_add_u64 v[46:47], v[96:97], 0, v[12:13]
	v_add_co_u32_e32 v60, vcc, s29, v46
	global_load_dwordx4 v[16:19], v[46:47], off nt
	global_load_dwordx4 v[24:27], v[46:47], off offset:1024 nt
	global_load_dwordx4 v[68:71], v[46:47], off offset:2048 nt
	global_load_dwordx4 v[34:37], v[46:47], off offset:3072 nt
	v_addc_co_u32_e32 v61, vcc, 0, v47, vcc
	global_load_dwordx2 v[210:211], v[44:45], off offset:3584 nt
	s_nop 0
	global_load_dwordx4 v[44:47], v[60:61], off nt
	global_load_dwordx4 v[52:55], v[60:61], off offset:1024 nt
	global_load_dwordx4 v[64:67], v[60:61], off offset:2048 nt
	s_nop 0
	global_load_dwordx4 v[60:63], v[60:61], off offset:3072 nt
	s_waitcnt vmcnt(28)
	v_and_b32_e32 v141, 0xffff0000, v110
	s_waitcnt vmcnt(23)
	v_lshlrev_b32_e32 v140, 16, v122
	v_and_b32_e32 v143, 0xffff0000, v122
	v_mov_b32_e32 v142, v141
	v_and_b32_e32 v203, 0xffff0000, v32
	v_lshlrev_b32_e32 v32, 16, v108
	v_and_b32_e32 v167, 0xffff0000, v108
	v_lshlrev_b32_e32 v164, 16, v109
	v_and_b32_e32 v169, 0xffff0000, v109
	v_lshlrev_b32_e32 v152, 16, v110
	v_lshlrev_b32_e32 v144, 16, v123
	v_mov_b32_e32 v153, v140
	v_pk_mul_f32 v[108:109], v[142:143], v[142:143]
	v_lshlrev_b32_e32 v154, 16, v111
	v_and_b32_e32 v145, 0xffff0000, v111
	v_pk_fma_f32 v[108:109], v[152:153], v[152:153], v[108:109]
	v_mov_b32_e32 v155, v144
	v_and_b32_e32 v159, 0xffff0000, v118
	v_and_b32_e32 v147, 0xffff0000, v123
	v_pk_fma_f32 v[108:109], v[154:155], v[154:155], v[108:109]
	v_mov_b32_e32 v146, v145
	v_pk_fma_f32 v[122:123], v[146:147], v[146:147], v[108:109]
	s_waitcnt vmcnt(22)
	v_lshlrev_b32_e32 v146, 16, v124
	v_and_b32_e32 v149, 0xffff0000, v124
	v_mov_b32_e32 v148, v159
	v_lshlrev_b32_e32 v156, 16, v118
	v_lshlrev_b32_e32 v142, 16, v125
	v_mov_b32_e32 v157, v146
	v_pk_mul_f32 v[108:109], v[148:149], v[148:149]
	v_lshlrev_b32_e32 v178, 16, v38
	v_and_b32_e32 v183, 0xffff0000, v38
	v_lshlrev_b32_e32 v180, 16, v39
	v_and_b32_e32 v193, 0xffff0000, v39
	v_lshlrev_b32_e32 v38, 16, v119
	v_and_b32_e32 v161, 0xffff0000, v119
	v_pk_fma_f32 v[108:109], v[156:157], v[156:157], v[108:109]
	v_mov_b32_e32 v39, v142
	v_and_b32_e32 v151, 0xffff0000, v125
	v_pk_fma_f32 v[108:109], v[38:39], v[38:39], v[108:109]
	v_mov_b32_e32 v150, v161
	s_waitcnt vmcnt(15)
	v_and_b32_e32 v111, 0xffff0000, v128
	v_pk_fma_f32 v[214:215], v[150:151], v[150:151], v[108:109]
	v_mov_b32_e32 v108, v111
	v_lshlrev_b32_e32 v206, 16, v112
	v_and_b32_e32 v179, 0xffff0000, v112
	v_lshlrev_b32_e32 v170, 16, v116
	v_and_b32_e32 v173, 0xffff0000, v116
	v_lshlrev_b32_e32 v162, 16, v117
	v_and_b32_e32 v175, 0xffff0000, v117
	v_lshlrev_b32_e32 v126, 16, v128
	v_lshlrev_b32_e32 v196, 16, v113
	v_and_b32_e32 v181, 0xffff0000, v113
	v_lshlrev_b32_e32 v128, 16, v129
	v_and_b32_e32 v113, 0xffff0000, v129
	v_lshlrev_b32_e32 v200, 16, v33
	v_and_b32_e32 v205, 0xffff0000, v33
	v_lshlrev_b32_e32 v194, 16, v114
	v_and_b32_e32 v33, 0xffff0000, v114
	v_lshlrev_b32_e32 v176, 16, v115
	v_and_b32_e32 v165, 0xffff0000, v115
	v_mov_b32_e32 v114, v113
	v_and_b32_e32 v221, 0xffff0000, v120
	v_and_b32_e32 v239, 0xffff0000, v14
	v_lshlrev_b32_e32 v220, 16, v120
	v_lshlrev_b32_e32 v238, 16, v14
	v_mov_b32_e32 v202, v179
	s_waitcnt vmcnt(14)
	v_lshlrev_b32_e32 v130, 16, v136
	v_and_b32_e32 v133, 0xffff0000, v136
	v_lshlrev_b32_e32 v124, 16, v137
	s_waitcnt vmcnt(11)
	v_lshlrev_b32_e32 v110, 16, v138
	v_and_b32_e32 v109, 0xffff0000, v138
	v_lshlrev_b32_e32 v112, 16, v139
	v_mov_b32_e32 v127, v110
	v_pk_mul_f32 v[116:117], v[108:109], v[108:109]
	v_mov_b32_e32 v129, v112
	v_pk_fma_f32 v[116:117], v[126:127], v[126:127], v[116:117]
	v_and_b32_e32 v115, 0xffff0000, v139
	v_pk_fma_f32 v[116:117], v[128:129], v[128:129], v[116:117]
	v_and_b32_e32 v135, 0xffff0000, v137
	v_pk_fma_f32 v[136:137], v[114:115], v[114:115], v[116:117]
	s_waitcnt vmcnt(4)
	v_lshlrev_b32_e32 v114, 16, v210
	v_and_b32_e32 v117, 0xffff0000, v210
	v_lshlrev_b32_e32 v108, 16, v211
	v_and_b32_e32 v119, 0xffff0000, v211
	ds_read_b128 v[210:213], v209
	v_mov_b32_e32 v250, v221
	v_mov_b32_e32 v251, v239
	v_lshlrev_b32_e32 v216, 16, v121
	v_lshlrev_b32_e32 v218, 16, v15
	v_and_b32_e32 v219, 0xffff0000, v15
	v_mov_b32_e32 v207, v198
	v_pk_mul_f32 v[14:15], v[202:203], v[202:203]
	v_mov_b32_e32 v182, v33
	v_mov_b32_e32 v248, v220
	v_mov_b32_e32 v249, v238
	v_pk_mul_f32 v[250:251], v[250:251], v[250:251]
	v_and_b32_e32 v217, 0xffff0000, v121
	v_pk_fma_f32 v[14:15], v[206:207], v[206:207], v[14:15]
	v_mov_b32_e32 v197, v200
	v_mov_b32_e32 v195, v178
	v_pk_mul_f32 v[120:121], v[182:183], v[182:183]
	v_mov_b32_e32 v166, v173
	v_mov_b32_e32 v244, v216
	v_mov_b32_e32 v245, v218
	v_pk_fma_f32 v[248:249], v[248:249], v[248:249], v[250:251]
	v_pk_fma_f32 v[14:15], v[196:197], v[196:197], v[14:15]
	v_mov_b32_e32 v204, v181
	v_pk_fma_f32 v[120:121], v[194:195], v[194:195], v[120:121]
	v_mov_b32_e32 v177, v180
	v_mov_b32_e32 v171, v32
	v_pk_mul_f32 v[240:241], v[166:167], v[166:167]
	v_mov_b32_e32 v246, v217
	v_mov_b32_e32 v247, v219
	v_pk_fma_f32 v[244:245], v[244:245], v[244:245], v[248:249]
	v_mov_b32_e32 v116, v133
	v_pk_fma_f32 v[14:15], v[204:205], v[204:205], v[14:15]
	v_pk_fma_f32 v[120:121], v[176:177], v[176:177], v[120:121]
	v_mov_b32_e32 v192, v165
	v_pk_fma_f32 v[240:241], v[170:171], v[170:171], v[240:241]
	v_mov_b32_e32 v163, v164
	v_pk_fma_f32 v[244:245], v[246:247], v[246:247], v[244:245]
	v_mov_b32_e32 v131, v114
	v_pk_mul_f32 v[138:139], v[116:117], v[116:117]
	v_pk_fma_f32 v[120:121], v[192:193], v[192:193], v[120:121]
	v_pk_fma_f32 v[240:241], v[162:163], v[162:163], v[240:241]
	v_mov_b32_e32 v168, v175
	v_pk_add_f32 v[14:15], v[244:245], v[14:15]
	v_pk_fma_f32 v[138:139], v[130:131], v[130:131], v[138:139]
	v_mov_b32_e32 v125, v108
	v_pk_fma_f32 v[240:241], v[168:169], v[168:169], v[240:241]
	v_pk_add_f32 v[14:15], v[14:15], v[120:121]
	v_pk_fma_f32 v[138:139], v[124:125], v[124:125], v[138:139]
	v_mov_b32_e32 v118, v135
	v_pk_add_f32 v[14:15], v[14:15], v[240:241]
	v_mov_b32_e32 v120, v214
	v_mov_b32_e32 v121, v122
	v_pk_fma_f32 v[138:139], v[118:119], v[118:119], v[138:139]
	v_pk_add_f32 v[14:15], v[14:15], v[120:121]
	v_mov_b32_e32 v122, v215
	v_pk_add_f32 v[14:15], v[14:15], v[122:123]
	v_mov_b32_e32 v120, v138
	v_mov_b32_e32 v121, v136
	v_pk_add_f32 v[14:15], v[14:15], v[120:121]
	v_mov_b32_e32 v136, v139
	v_pk_add_f32 v[14:15], v[14:15], v[136:137]
	v_lshl_add_u64 v[122:123], v[102:103], 0, v[186:187]
	v_mov_b32_e32 v121, v15
	v_mov_b32_e32 v120, v14
	s_nop 1
	v_permlane32_swap_b32_e32 v121, v15
	v_permlane32_swap_b32_e32 v120, v14
	v_add_f32_e32 v15, v15, v121
	v_add_f32_e32 v14, v14, v120
	v_mov_b32_e32 v121, v15
	v_mov_b32_e32 v120, v14
	s_nop 1
	v_permlane16_swap_b32_e32 v121, v15
	v_permlane16_swap_b32_e32 v120, v14
	v_add_f32_e32 v15, v15, v121
	v_add_f32_e32 v14, v14, v120
	s_nop 1
	v_add_f32_dpp v14, v14, v14 row_mirror row_mask:0xf bank_mask:0xf
	v_add_f32_dpp v15, v15, v15 row_mirror row_mask:0xf bank_mask:0xf
	s_nop 1
	v_add_f32_dpp v14, v14, v14 row_half_mirror row_mask:0xf bank_mask:0xf
	v_add_f32_dpp v15, v15, v15 row_half_mirror row_mask:0xf bank_mask:0xf
	s_nop 1
	v_add_f32_dpp v14, v14, v14 quad_perm:[2,3,0,1] row_mask:0xf bank_mask:0xf
	v_add_f32_dpp v15, v15, v15 quad_perm:[2,3,0,1] row_mask:0xf bank_mask:0xf
	s_nop 1
	v_add_f32_dpp v14, v14, v14 quad_perm:[1,0,3,2] row_mask:0xf bank_mask:0xf
	v_add_f32_dpp v15, v15, v15 quad_perm:[1,0,3,2] row_mask:0xf bank_mask:0xf
	s_nop 0
	v_pk_fma_f32 v[14:15], v[14:15], s[34:35], v[188:189] op_sel_hi:[1,0,0]
	v_lshl_add_u64 v[120:121], v[98:99], 0, v[12:13]
	v_mul_f32_e32 v39, 0x4b800000, v15
	v_cmp_gt_f32_e32 vcc, s80, v15
	s_nop 1
	v_cndmask_b32_e32 v15, v15, v39, vcc
	v_rsq_f32_e32 v15, v15
	s_nop 0
	v_mul_f32_e32 v12, 0x45800000, v15
	v_cndmask_b32_e32 v138, v15, v12, vcc
	v_mul_f32_e32 v15, 0x4b800000, v14
	v_cmp_gt_f32_e32 vcc, s80, v14
	v_pk_mul_f32 v[12:13], v[138:139], v[238:239] op_sel_hi:[0,1]
	s_waitcnt vmcnt(0) lgkmcnt(0)
	v_pk_fma_f32 v[12:13], v[210:211], v[12:13], v[4:5]
	v_cndmask_b32_e32 v14, v14, v15, vcc
	v_rsq_f32_e32 v39, v14
	v_pk_mul_f32 v[14:15], v[138:139], v[218:219] op_sel_hi:[0,1]
	v_pk_fma_f32 v[14:15], v[212:213], v[14:15], v[6:7]
	global_store_dwordx4 v[122:123], v[12:15], off
	v_mul_f32_e32 v4, 0x45800000, v39
	v_cndmask_b32_e32 v136, v39, v4, vcc
	v_pk_mul_f32 v[4:5], v[136:137], v[220:221] op_sel_hi:[0,1]
	v_pk_mul_f32 v[6:7], v[136:137], v[216:217] op_sel_hi:[0,1]
	v_pk_fma_f32 v[4:5], v[210:211], v[4:5], v[16:17]
	v_pk_fma_f32 v[6:7], v[212:213], v[6:7], v[18:19]
	s_and_saveexec_b64 s[4:5], s[10:11]
	s_cbranch_execz .LBB0_134
	global_store_dwordx4 v[120:121], v[4:7], off

.LBB0_148:
	s_or_b64 exec, exec, s[4:5]
	v_mov_b32_e32 v62, v5
	v_mov_b32_e32 v63, v13
	v_mov_b32_e32 v60, v4
	v_mov_b32_e32 v61, v12
	v_pk_mul_f32 v[62:63], v[62:63], v[62:63]
	v_mov_b32_e32 v68, v1
	v_pk_fma_f32 v[60:61], v[60:61], v[60:61], v[62:63]
	v_mov_b32_e32 v62, v6
	v_mov_b32_e32 v63, v14
	v_pk_fma_f32 v[60:61], v[62:63], v[62:63], v[60:61]
	v_mov_b32_e32 v62, v7
	v_mov_b32_e32 v63, v15
	v_mov_b32_e32 v69, v17
	v_pk_fma_f32 v[60:61], v[62:63], v[62:63], v[60:61]
	v_mov_b32_e32 v62, v0
	v_mov_b32_e32 v63, v16
	v_pk_mul_f32 v[68:69], v[68:69], v[68:69]
	v_pk_mul_f32 v[70:71], v[56:57], v[56:57]
	v_pk_fma_f32 v[62:63], v[62:63], v[62:63], v[68:69]
	v_mov_b32_e32 v68, v2
	v_mov_b32_e32 v69, v18
	v_pk_fma_f32 v[62:63], v[68:69], v[68:69], v[62:63]
	v_mov_b32_e32 v68, v3
	v_mov_b32_e32 v69, v19
	v_pk_fma_f32 v[62:63], v[68:69], v[68:69], v[62:63]
	v_mov_b32_e32 v68, v9
	v_mov_b32_e32 v69, v25
	v_pk_add_f32 v[60:61], v[60:61], v[62:63]
	v_mov_b32_e32 v62, v8
	v_mov_b32_e32 v63, v24
	v_pk_mul_f32 v[68:69], v[68:69], v[68:69]
	v_mov_b32_e32 v108, v70
	v_pk_fma_f32 v[62:63], v[62:63], v[62:63], v[68:69]
	v_mov_b32_e32 v68, v10
	v_mov_b32_e32 v69, v26
	v_pk_fma_f32 v[62:63], v[68:69], v[68:69], v[62:63]
	v_mov_b32_e32 v68, v11
	v_mov_b32_e32 v69, v27
	v_pk_fma_f32 v[62:63], v[68:69], v[68:69], v[62:63]
	v_mov_b32_e32 v68, v21
	v_mov_b32_e32 v69, v33
	v_pk_add_f32 v[60:61], v[60:61], v[62:63]
	v_mov_b32_e32 v62, v20
	v_mov_b32_e32 v63, v32
	v_pk_mul_f32 v[68:69], v[68:69], v[68:69]
	s_nop 0
	v_pk_fma_f32 v[62:63], v[62:63], v[62:63], v[68:69]
	v_mov_b32_e32 v68, v22
	v_mov_b32_e32 v69, v34
	v_pk_fma_f32 v[62:63], v[68:69], v[68:69], v[62:63]
	v_mov_b32_e32 v68, v23
	v_mov_b32_e32 v69, v35
	v_pk_fma_f32 v[62:63], v[68:69], v[68:69], v[62:63]
	v_mov_b32_e32 v68, v29
	v_mov_b32_e32 v69, v37
	v_pk_add_f32 v[60:61], v[60:61], v[62:63]
	v_mov_b32_e32 v62, v28
	v_mov_b32_e32 v63, v36
	v_pk_mul_f32 v[68:69], v[68:69], v[68:69]
	s_nop 0
	v_pk_fma_f32 v[62:63], v[62:63], v[62:63], v[68:69]
	v_mov_b32_e32 v68, v30
	v_mov_b32_e32 v69, v38
	v_pk_fma_f32 v[62:63], v[68:69], v[68:69], v[62:63]
	v_mov_b32_e32 v68, v31
	v_mov_b32_e32 v69, v39
	v_pk_fma_f32 v[62:63], v[68:69], v[68:69], v[62:63]
	v_mov_b32_e32 v68, v41
	v_mov_b32_e32 v69, v45
	v_pk_add_f32 v[60:61], v[60:61], v[62:63]
	v_mov_b32_e32 v62, v40
	v_mov_b32_e32 v63, v44
	v_pk_mul_f32 v[68:69], v[68:69], v[68:69]
	s_nop 0
	v_pk_fma_f32 v[62:63], v[62:63], v[62:63], v[68:69]
	v_mov_b32_e32 v68, v42
	v_mov_b32_e32 v69, v46
	v_pk_fma_f32 v[62:63], v[68:69], v[68:69], v[62:63]
	v_mov_b32_e32 v68, v43
	v_mov_b32_e32 v69, v47
	v_pk_fma_f32 v[62:63], v[68:69], v[68:69], v[62:63]
	v_mov_b32_e32 v68, v49
	v_mov_b32_e32 v69, v53
	v_pk_add_f32 v[60:61], v[60:61], v[62:63]
	v_mov_b32_e32 v62, v48
	v_mov_b32_e32 v63, v52
	v_pk_mul_f32 v[68:69], v[68:69], v[68:69]
	s_nop 0
	v_pk_fma_f32 v[62:63], v[62:63], v[62:63], v[68:69]
	v_mov_b32_e32 v68, v50
	v_mov_b32_e32 v69, v54
	v_pk_fma_f32 v[62:63], v[68:69], v[68:69], v[62:63]
	v_mov_b32_e32 v68, v51
	v_mov_b32_e32 v69, v55
	v_pk_fma_f32 v[62:63], v[68:69], v[68:69], v[62:63]
	v_pk_mul_f32 v[68:69], v[66:67], v[66:67]
	v_pk_add_f32 v[60:61], v[60:61], v[62:63]
	v_pk_mul_f32 v[62:63], v[64:65], v[64:65]
	s_nop 0
	v_mov_b32_e32 v109, v62
	v_mov_b32_e32 v62, v71
	v_pk_mul_f32 v[70:71], v[58:59], v[58:59]
	v_pk_add_f32 v[62:63], v[108:109], v[62:63]
	v_mov_b32_e32 v108, v70
	v_mov_b32_e32 v109, v68
	v_pk_add_f32 v[62:63], v[62:63], v[108:109]
	v_mov_b32_e32 v68, v71
	v_pk_add_f32 v[62:63], v[68:69], v[62:63]
	v_lshl_add_u64 v[68:69], v[78:79], 0, v[106:107]
	v_pk_add_f32 v[60:61], v[60:61], v[62:63]
	v_mov_b32_e32 v63, v61
	v_mov_b32_e32 v62, v60
	s_nop 1
	v_permlane32_swap_b32_e32 v63, v61
	v_permlane32_swap_b32_e32 v62, v60
	v_add_f32_e32 v61, v61, v63
	v_add_f32_e32 v60, v60, v62
	v_mov_b32_e32 v63, v61
	v_mov_b32_e32 v62, v60
	s_nop 1
	v_permlane16_swap_b32_e32 v63, v61
	v_permlane16_swap_b32_e32 v62, v60
	v_add_f32_e32 v61, v61, v63
	v_add_f32_e32 v60, v60, v62
	s_nop 1
	v_add_f32_dpp v60, v60, v60 row_mirror row_mask:0xf bank_mask:0xf
	v_add_f32_dpp v61, v61, v61 row_mirror row_mask:0xf bank_mask:0xf
	s_nop 1
	v_add_f32_dpp v60, v60, v60 row_half_mirror row_mask:0xf bank_mask:0xf
	v_add_f32_dpp v61, v61, v61 row_half_mirror row_mask:0xf bank_mask:0xf
	s_nop 1
	v_add_f32_dpp v60, v60, v60 quad_perm:[2,3,0,1] row_mask:0xf bank_mask:0xf
	v_add_f32_dpp v61, v61, v61 quad_perm:[2,3,0,1] row_mask:0xf bank_mask:0xf
	s_nop 1
	v_add_f32_dpp v60, v60, v60 quad_perm:[1,0,3,2] row_mask:0xf bank_mask:0xf
	v_add_f32_dpp v61, v61, v61 quad_perm:[1,0,3,2] row_mask:0xf bank_mask:0xf
	s_nop 0
	v_pk_fma_f32 v[60:61], v[60:61], s[34:35], v[188:189] op_sel_hi:[1,0,0]
	s_nop 0
	v_mul_f32_e32 v62, 0x4b800000, v61
	v_cmp_gt_f32_e64 s[12:13], s80, v61
	v_cmp_gt_f32_e32 vcc, s80, v60
	s_nop 0
	v_cndmask_b32_e64 v61, v61, v62, s[12:13]
	v_rsq_f32_e32 v61, v61
	s_nop 0
	v_mul_f32_e32 v62, 0x45800000, v61
	v_cndmask_b32_e64 v108, v61, v62, s[12:13]
	v_mul_f32_e32 v61, 0x4b800000, v60
	v_cndmask_b32_e32 v60, v60, v61, vcc
	v_rsq_f32_e32 v60, v60
	v_pk_mul_f32 v[12:13], v[12:13], v[108:109] op_sel_hi:[1,0]
	v_pk_mul_f32 v[14:15], v[14:15], v[108:109] op_sel_hi:[1,0]
	v_mul_f32_e32 v61, 0x45800000, v60
	v_cndmask_b32_e32 v70, v60, v61, vcc
	ds_read_b128 v[60:63], v209 offset:8192
	s_waitcnt lgkmcnt(0)
	v_pk_mul_f32 v[12:13], v[60:61], v[12:13]
	v_pk_mul_f32 v[14:15], v[62:63], v[14:15]
	v_cvt_pk_bf16_f32 v12, v12, v13
	v_cvt_pk_bf16_f32 v13, v14, v15
	v_add_co_u32_e32 v14, vcc, 0x4000000, v100
	s_nop 1
	v_addc_co_u32_e32 v15, vcc, 0, v101, vcc
	global_store_dwordx2 v[14:15], v[12:13], off
	s_and_saveexec_b64 s[4:5], s[10:11]
	s_cbranch_execz .LBB0_150
	v_pk_mul_f32 v[4:5], v[4:5], v[70:71] op_sel_hi:[1,0]
	v_pk_mul_f32 v[6:7], v[6:7], v[70:71] op_sel_hi:[1,0]
	v_pk_mul_f32 v[4:5], v[60:61], v[4:5]
	v_pk_mul_f32 v[6:7], v[62:63], v[6:7]
	v_cvt_pk_bf16_f32 v4, v4, v5
	v_cvt_pk_bf16_f32 v5, v6, v7
	global_store_dwordx2 v[68:69], v[4:5], off

.LBB0_180:
	s_ashr_i32 s31, s30, 31
	s_lshl_b64 s[4:5], s[30:31], 11
	s_waitcnt vmcnt(1)
	v_lshl_add_u64 v[8:9], s[4:5], 0, v[68:69]
	v_lshlrev_b64 v[72:73], 1, v[8:9]
	v_lshl_add_u64 v[8:9], s[0:1], 0, v[72:73]
	global_load_dwordx4 v[64:67], v[8:9], off nt
	v_lshl_add_u64 v[72:73], s[2:3], 0, v[72:73]
	global_load_dwordx4 v[80:83], v[72:73], off nt
	s_add_i32 s4, s30, s64
	s_cmpk_lt_i32 s4, 0x2000
	s_cselect_b32 s6, s4, s30
	s_ashr_i32 s7, s6, 31
	s_lshl_b64 s[34:35], s[6:7], 11
	v_lshl_add_u64 v[8:9], s[34:35], 0, v[68:69]
	v_lshlrev_b64 v[8:9], 1, v[8:9]
	v_lshl_add_u64 v[10:11], s[0:1], 0, v[8:9]
	global_load_dwordx4 v[60:63], v[10:11], off nt
	s_add_i32 s26, s53, s30
	s_cmpk_lt_i32 s26, 0x2000
	s_cselect_b64 s[28:29], -1, 0
	s_and_b64 s[6:7], s[28:29], exec
	s_cselect_b32 s6, s26, s30
	s_ashr_i32 s7, s6, 31
	v_readlane_b32 s5, v254, 40
	s_lshl_b64 s[36:37], s[6:7], 11
	s_add_i32 s22, s5, s30
	s_cmpk_lt_i32 s22, 0x2000
	s_cselect_b64 s[24:25], -1, 0
	s_and_b64 s[6:7], s[24:25], exec
	s_cselect_b32 s6, s22, s30
	s_ashr_i32 s7, s6, 31
	s_lshl_b64 s[38:39], s[6:7], 11
	s_add_i32 s18, s55, s30
	s_cmpk_lt_i32 s18, 0x2000
	s_cselect_b64 s[20:21], -1, 0
	s_and_b64 s[6:7], s[20:21], exec
	s_cselect_b32 s6, s18, s30
	s_ashr_i32 s7, s6, 31
	v_readlane_b32 s5, v254, 41
	s_lshl_b64 s[40:41], s[6:7], 11
	s_add_i32 s14, s5, s30
	s_cmpk_lt_i32 s14, 0x2000
	s_cselect_b64 s[16:17], -1, 0
	s_and_b64 s[6:7], s[16:17], exec
	v_lshl_add_u64 v[8:9], s[2:3], 0, v[8:9]
	s_cselect_b32 s6, s14, s30
	global_load_dwordx4 v[56:59], v[8:9], off nt
	v_lshl_add_u64 v[8:9], s[36:37], 0, v[68:69]
	s_ashr_i32 s7, s6, 31
	v_readlane_b32 s5, v254, 42
	v_lshlrev_b64 v[8:9], 1, v[8:9]
	s_lshl_b64 s[42:43], s[6:7], 11
	s_add_i32 s10, s5, s30
	v_lshl_add_u64 v[10:11], s[0:1], 0, v[8:9]
	v_lshl_add_u64 v[8:9], s[2:3], 0, v[8:9]
	s_cmpk_lt_i32 s10, 0x2000
	global_load_dwordx4 v[48:51], v[8:9], off nt
	v_lshl_add_u64 v[8:9], s[38:39], 0, v[68:69]
	s_cselect_b64 s[12:13], -1, 0
	v_lshlrev_b64 v[8:9], 1, v[8:9]
	s_and_b64 s[6:7], s[12:13], exec
	global_load_dwordx4 v[52:55], v[10:11], off nt
	v_lshl_add_u64 v[10:11], s[0:1], 0, v[8:9]
	v_lshl_add_u64 v[8:9], s[2:3], 0, v[8:9]
	s_cselect_b32 s6, s10, s30
	global_load_dwordx4 v[40:43], v[8:9], off nt
	v_lshl_add_u64 v[8:9], s[40:41], 0, v[68:69]
	s_ashr_i32 s7, s6, 31
	v_readlane_b32 s5, v254, 43
	v_lshlrev_b64 v[8:9], 1, v[8:9]
	s_lshl_b64 s[44:45], s[6:7], 11
	s_add_i32 s6, s5, s30
	global_load_dwordx4 v[44:47], v[10:11], off nt
	v_lshl_add_u64 v[10:11], s[0:1], 0, v[8:9]
	v_lshl_add_u64 v[8:9], s[2:3], 0, v[8:9]
	s_cmpk_lt_i32 s6, 0x2000
	global_load_dwordx4 v[32:35], v[8:9], off nt
	v_lshl_add_u64 v[8:9], s[42:43], 0, v[68:69]
	s_cselect_b64 s[8:9], -1, 0
	v_lshlrev_b64 v[8:9], 1, v[8:9]
	s_and_b64 s[46:47], s[8:9], exec
	global_load_dwordx4 v[36:39], v[10:11], off nt
	v_lshl_add_u64 v[10:11], s[0:1], 0, v[8:9]
	v_lshl_add_u64 v[8:9], s[2:3], 0, v[8:9]
	s_cselect_b32 s46, s6, s30
	s_waitcnt vmcnt(9)
	v_lshlrev_b32_e32 v84, 16, v64
	v_and_b32_e32 v85, 0xffff0000, v64
	v_pk_mul_f32 v[86:87], v[84:85], v[84:85]
	v_lshlrev_b32_e32 v64, 16, v65
	v_and_b32_e32 v65, 0xffff0000, v65
	v_pk_mul_f32 v[88:89], v[64:65], v[64:65]
	s_waitcnt vmcnt(8)
	v_lshlrev_b32_e32 v90, 16, v81
	v_and_b32_e32 v91, 0xffff0000, v81
	v_add_f32_e32 v81, v86, v87
	v_lshlrev_b32_e32 v92, 16, v66
	v_and_b32_e32 v93, 0xffff0000, v66
	v_add_f32_e32 v81, v88, v81
	v_pk_mul_f32 v[94:95], v[92:93], v[92:93]
	v_add_f32_e32 v81, v89, v81
	v_lshlrev_b32_e32 v66, 16, v67
	v_and_b32_e32 v67, 0xffff0000, v67
	v_add_f32_e32 v81, v94, v81
	v_pk_mul_f32 v[98:99], v[66:67], v[66:67]
	v_add_f32_e32 v81, v95, v81
	v_add_f32_e32 v81, v98, v81
	v_add_f32_e32 v81, v99, v81
	global_load_dwordx4 v[24:27], v[8:9], off nt
	v_lshl_add_u64 v[8:9], s[44:45], 0, v[68:69]
	s_ashr_i32 s47, s46, 31
	v_lshlrev_b64 v[8:9], 1, v[8:9]
	v_mov_b32_e32 v86, v81
	s_nop 1
	v_permlane32_swap_b32_e32 v86, v81
	v_add_f32_e32 v81, v81, v86
	s_lshl_b64 s[46:47], s[46:47], 11
	global_load_dwordx4 v[28:31], v[10:11], off nt
	v_lshl_add_u64 v[10:11], s[0:1], 0, v[8:9]
	v_lshl_add_u64 v[8:9], s[2:3], 0, v[8:9]
	v_mov_b32_e32 v86, v81
	s_nop 1
	v_permlane16_swap_b32_e32 v86, v81
	v_add_f32_e32 v81, v81, v86
	global_load_dwordx4 v[16:19], v[8:9], off nt
	v_lshl_add_u64 v[8:9], s[46:47], 0, v[68:69]
	v_lshlrev_b64 v[8:9], 1, v[8:9]
	global_load_dwordx4 v[20:23], v[10:11], off nt
	v_lshl_add_u64 v[10:11], s[0:1], 0, v[8:9]
	v_lshl_add_u64 v[8:9], s[2:3], 0, v[8:9]
	s_nop 1
	v_add_f32_dpp v81, v81, v81 row_mirror row_mask:0xf bank_mask:0xf
	global_load_dwordx4 v[12:15], v[10:11], off nt
	global_load_dwordx4 v[8:11], v[8:9], off nt
	v_lshlrev_b32_e32 v96, 16, v82
	v_and_b32_e32 v97, 0xffff0000, v82
	v_lshlrev_b32_e32 v82, 16, v83
	s_nop 1
	v_add_f32_dpp v81, v81, v81 row_half_mirror row_mask:0xf bank_mask:0xf
	v_and_b32_e32 v83, 0xffff0000, v83
	s_lshl_b64 s[30:31], s[30:31], 12
	v_lshl_add_u64 v[72:73], v[70:71], 0, s[30:31]
	s_cmpk_gt_i32 s4, 0x1fff
	s_nop 1
	v_add_f32_dpp v81, v81, v81 quad_perm:[2,3,0,1] row_mask:0xf bank_mask:0xf
	s_nop 1
	v_add_f32_dpp v81, v81, v81 quad_perm:[1,0,3,2] row_mask:0xf bank_mask:0xf
	v_fmamk_f32 v81, v81, 0x3b000000, v188
	v_cmp_gt_f32_e32 vcc, s80, v81
	v_mul_f32_e32 v86, 0x4b800000, v81
	s_nop 0
	v_cndmask_b32_e32 v81, v81, v86, vcc
	v_rsq_f32_e32 v81, v81
	s_nop 0
	v_mul_f32_e32 v86, 0x45800000, v81
	v_cndmask_b32_e32 v86, v81, v86, vcc
	v_pk_mul_f32 v[66:67], v[86:87], v[66:67] op_sel_hi:[0,1]
	v_pk_mul_f32 v[66:67], v[2:3], v[66:67]
	v_pk_mul_f32 v[64:65], v[86:87], v[64:65] op_sel_hi:[0,1]
	v_pk_mul_f32 v[66:67], v[66:67], v[82:83]
	v_pk_mul_f32 v[82:83], v[86:87], v[92:93] op_sel_hi:[0,1]
	v_pk_mul_f32 v[82:83], v[0:1], v[82:83]
	v_cvt_pk_bf16_f32 v67, v66, v67
	v_pk_mul_f32 v[82:83], v[82:83], v[96:97]
	v_pk_mul_f32 v[64:65], v[6:7], v[64:65]
	v_cvt_pk_bf16_f32 v66, v82, v83
	v_pk_mul_f32 v[82:83], v[86:87], v[84:85] op_sel_hi:[0,1]
	v_pk_mul_f32 v[82:83], v[4:5], v[82:83]
	v_lshlrev_b32_e32 v84, 16, v80
	v_and_b32_e32 v85, 0xffff0000, v80
	v_pk_mul_f32 v[64:65], v[64:65], v[90:91]
	v_pk_mul_f32 v[80:81], v[82:83], v[84:85]
	v_cvt_pk_bf16_f32 v65, v64, v65
	v_cvt_pk_bf16_f32 v64, v80, v81
	global_store_dwordx4 v[72:73], v[64:67], off
	s_waitcnt vmcnt(14)
	s_nop 0
	v_lshlrev_b32_e32 v64, 16, v60
	v_and_b32_e32 v65, 0xffff0000, v60
	v_lshlrev_b32_e32 v60, 16, v61
	v_and_b32_e32 v61, 0xffff0000, v61
	v_pk_mul_f32 v[72:73], v[64:65], v[64:65]
	v_pk_mul_f32 v[80:81], v[60:61], v[60:61]
	v_add_f32_e32 v72, v72, v73
	v_lshlrev_b32_e32 v66, 16, v62
	v_and_b32_e32 v67, 0xffff0000, v62
	v_add_f32_e32 v72, v80, v72
	v_pk_mul_f32 v[82:83], v[66:67], v[66:67]
	v_add_f32_e32 v72, v81, v72
	v_lshlrev_b32_e32 v62, 16, v63
	v_and_b32_e32 v63, 0xffff0000, v63
	v_add_f32_e32 v72, v82, v72
	v_pk_mul_f32 v[84:85], v[62:63], v[62:63]
	v_add_f32_e32 v72, v83, v72
	v_add_f32_e32 v72, v84, v72
	v_add_f32_e32 v72, v85, v72
	v_mov_b32_e32 v73, v72
	s_nop 1
	v_permlane32_swap_b32_e32 v73, v72
	v_add_f32_e32 v72, v72, v73
	v_mov_b32_e32 v73, v72
	s_nop 1
	v_permlane16_swap_b32_e32 v73, v72
	v_add_f32_e32 v72, v72, v73
	s_nop 1
	v_add_f32_dpp v72, v72, v72 row_mirror row_mask:0xf bank_mask:0xf
	s_nop 1
	v_add_f32_dpp v72, v72, v72 row_half_mirror row_mask:0xf bank_mask:0xf
	s_nop 1
	v_add_f32_dpp v72, v72, v72 quad_perm:[2,3,0,1] row_mask:0xf bank_mask:0xf
	ds_bpermute_b32 v73, v79, v72
	s_cbranch_scc1 .LBB0_182
	s_waitcnt lgkmcnt(0)
	v_add_f32_e32 v72, v72, v73
	v_fmamk_f32 v72, v72, 0x3b000000, v188
	v_cmp_gt_f32_e32 vcc, s80, v72
	v_mul_f32_e32 v73, 0x4b800000, v72
	s_waitcnt vmcnt(13)
	v_lshlrev_b32_e32 v82, 16, v59
	v_cndmask_b32_e32 v72, v72, v73, vcc
	v_rsq_f32_e32 v72, v72
	v_and_b32_e32 v83, 0xffff0000, v59
	s_ashr_i32 s5, s4, 31
	s_lshl_b64 s[30:31], s[4:5], 12
	v_mul_f32_e32 v73, 0x45800000, v72
	v_cndmask_b32_e32 v72, v72, v73, vcc
	v_pk_mul_f32 v[62:63], v[72:73], v[62:63] op_sel_hi:[0,1]
	v_pk_mul_f32 v[62:63], v[2:3], v[62:63]
	v_pk_mul_f32 v[60:61], v[72:73], v[60:61] op_sel_hi:[0,1]
	v_pk_mul_f32 v[62:63], v[62:63], v[82:83]
	v_pk_mul_f32 v[60:61], v[6:7], v[60:61]
	v_cvt_pk_bf16_f32 v59, v62, v63
	v_pk_mul_f32 v[62:63], v[72:73], v[66:67] op_sel_hi:[0,1]
	v_pk_mul_f32 v[62:63], v[0:1], v[62:63]
	v_lshlrev_b32_e32 v66, 16, v58
	v_and_b32_e32 v67, 0xffff0000, v58
	v_pk_mul_f32 v[62:63], v[62:63], v[66:67]
	v_lshl_add_u64 v[80:81], v[70:71], 0, s[30:31]
	v_cvt_pk_bf16_f32 v58, v62, v63
	v_lshlrev_b32_e32 v62, 16, v57
	v_and_b32_e32 v63, 0xffff0000, v57
	v_pk_mul_f32 v[60:61], v[60:61], v[62:63]
	v_lshlrev_b32_e32 v62, 16, v56
	v_cvt_pk_bf16_f32 v57, v60, v61
	v_pk_mul_f32 v[60:61], v[72:73], v[64:65] op_sel_hi:[0,1]
	v_pk_mul_f32 v[60:61], v[4:5], v[60:61]
	v_and_b32_e32 v63, 0xffff0000, v56
	v_pk_mul_f32 v[60:61], v[60:61], v[62:63]
	s_nop 0
	v_cvt_pk_bf16_f32 v56, v60, v61
	global_store_dwordx4 v[80:81], v[56:59], off
.LBB0_182:
	s_waitcnt vmcnt(11)
	s_nop 0
	v_lshlrev_b32_e32 v56, 16, v52
	v_and_b32_e32 v57, 0xffff0000, v52
	v_lshlrev_b32_e32 v52, 16, v53
	v_and_b32_e32 v53, 0xffff0000, v53
	v_pk_mul_f32 v[60:61], v[56:57], v[56:57]
	v_pk_mul_f32 v[62:63], v[52:53], v[52:53]
	v_add_f32_e32 v60, v60, v61
	v_lshlrev_b32_e32 v58, 16, v54
	v_and_b32_e32 v59, 0xffff0000, v54
	v_add_f32_e32 v60, v62, v60
	v_pk_mul_f32 v[64:65], v[58:59], v[58:59]
	v_add_f32_e32 v60, v63, v60
	v_lshlrev_b32_e32 v54, 16, v55
	v_and_b32_e32 v55, 0xffff0000, v55
	v_add_f32_e32 v60, v64, v60
	v_pk_mul_f32 v[66:67], v[54:55], v[54:55]
	v_add_f32_e32 v60, v65, v60
	v_add_f32_e32 v60, v66, v60
	v_add_f32_e32 v60, v67, v60
	s_andn2_b64 vcc, exec, s[28:29]
	v_mov_b32_e32 v61, v60
	s_nop 1
	v_permlane32_swap_b32_e32 v61, v60
	v_add_f32_e32 v60, v60, v61
	v_mov_b32_e32 v61, v60
	s_nop 1
	v_permlane16_swap_b32_e32 v61, v60
	v_add_f32_e32 v60, v60, v61
	s_nop 1
	v_add_f32_dpp v60, v60, v60 row_mirror row_mask:0xf bank_mask:0xf
	s_nop 1
	v_add_f32_dpp v60, v60, v60 row_half_mirror row_mask:0xf bank_mask:0xf
	s_nop 1
	v_add_f32_dpp v60, v60, v60 quad_perm:[2,3,0,1] row_mask:0xf bank_mask:0xf
	ds_bpermute_b32 v61, v79, v60
	s_cbranch_vccnz .LBB0_184
	s_waitcnt lgkmcnt(0)
	v_add_f32_e32 v60, v60, v61
	v_fmamk_f32 v60, v60, 0x3b000000, v188
	v_cmp_gt_f32_e32 vcc, s80, v60
	v_mul_f32_e32 v61, 0x4b800000, v60
	v_lshlrev_b32_e32 v64, 16, v51
	v_cndmask_b32_e32 v60, v60, v61, vcc
	v_rsq_f32_e32 v60, v60
	v_and_b32_e32 v65, 0xffff0000, v51
	s_ashr_i32 s27, s26, 31
	s_lshl_b64 s[26:27], s[26:27], 12
	v_mul_f32_e32 v61, 0x45800000, v60
	v_cndmask_b32_e32 v60, v60, v61, vcc
	v_pk_mul_f32 v[54:55], v[60:61], v[54:55] op_sel_hi:[0,1]
	v_pk_mul_f32 v[54:55], v[2:3], v[54:55]
	v_pk_mul_f32 v[58:59], v[60:61], v[58:59] op_sel_hi:[0,1]
	v_pk_mul_f32 v[54:55], v[54:55], v[64:65]
	v_pk_mul_f32 v[58:59], v[0:1], v[58:59]
	v_cvt_pk_bf16_f32 v51, v54, v55
	v_lshlrev_b32_e32 v54, 16, v50
	v_and_b32_e32 v55, 0xffff0000, v50
	v_pk_mul_f32 v[54:55], v[58:59], v[54:55]
	v_pk_mul_f32 v[52:53], v[60:61], v[52:53] op_sel_hi:[0,1]
	v_cvt_pk_bf16_f32 v50, v54, v55
	v_lshlrev_b32_e32 v54, 16, v49
	v_and_b32_e32 v55, 0xffff0000, v49
	v_pk_mul_f32 v[52:53], v[6:7], v[52:53]
	v_lshl_add_u64 v[62:63], v[70:71], 0, s[26:27]
	v_pk_mul_f32 v[52:53], v[52:53], v[54:55]
	v_pk_mul_f32 v[54:55], v[60:61], v[56:57] op_sel_hi:[0,1]
	v_cvt_pk_bf16_f32 v49, v52, v53
	v_lshlrev_b32_e32 v52, 16, v48
	v_and_b32_e32 v53, 0xffff0000, v48
	v_pk_mul_f32 v[54:55], v[4:5], v[54:55]
	s_nop 0
	v_pk_mul_f32 v[52:53], v[54:55], v[52:53]
	s_nop 0
	v_cvt_pk_bf16_f32 v48, v52, v53
	global_store_dwordx4 v[62:63], v[48:51], off
.LBB0_184:
	s_waitcnt vmcnt(9)
	s_nop 0
	v_lshlrev_b32_e32 v48, 16, v44
	v_and_b32_e32 v49, 0xffff0000, v44
	v_lshlrev_b32_e32 v44, 16, v45
	v_and_b32_e32 v45, 0xffff0000, v45
	v_pk_mul_f32 v[52:53], v[48:49], v[48:49]
	v_pk_mul_f32 v[54:55], v[44:45], v[44:45]
	v_add_f32_e32 v52, v52, v53
	v_lshlrev_b32_e32 v50, 16, v46
	v_and_b32_e32 v51, 0xffff0000, v46
	v_add_f32_e32 v52, v54, v52
	v_pk_mul_f32 v[56:57], v[50:51], v[50:51]
	v_add_f32_e32 v52, v55, v52
	v_lshlrev_b32_e32 v46, 16, v47
	v_and_b32_e32 v47, 0xffff0000, v47
	v_add_f32_e32 v52, v56, v52
	v_pk_mul_f32 v[58:59], v[46:47], v[46:47]
	v_add_f32_e32 v52, v57, v52
	v_add_f32_e32 v52, v58, v52
	v_add_f32_e32 v52, v59, v52
	s_andn2_b64 vcc, exec, s[24:25]
	v_mov_b32_e32 v53, v52
	s_nop 1
	v_permlane32_swap_b32_e32 v53, v52
	v_add_f32_e32 v52, v52, v53
	v_mov_b32_e32 v53, v52
	s_nop 1
	v_permlane16_swap_b32_e32 v53, v52
	v_add_f32_e32 v52, v52, v53
	s_nop 1
	v_add_f32_dpp v52, v52, v52 row_mirror row_mask:0xf bank_mask:0xf
	s_nop 1
	v_add_f32_dpp v52, v52, v52 row_half_mirror row_mask:0xf bank_mask:0xf
	s_nop 1
	v_add_f32_dpp v52, v52, v52 quad_perm:[2,3,0,1] row_mask:0xf bank_mask:0xf
	ds_bpermute_b32 v53, v79, v52
	s_cbranch_vccnz .LBB0_186
	s_waitcnt lgkmcnt(0)
	v_add_f32_e32 v52, v52, v53
	v_fmamk_f32 v52, v52, 0x3b000000, v188
	v_cmp_gt_f32_e32 vcc, s80, v52
	v_mul_f32_e32 v53, 0x4b800000, v52
	v_lshlrev_b32_e32 v56, 16, v43
	v_cndmask_b32_e32 v52, v52, v53, vcc
	v_rsq_f32_e32 v52, v52
	v_and_b32_e32 v57, 0xffff0000, v43
	s_ashr_i32 s23, s22, 31
	s_lshl_b64 s[22:23], s[22:23], 12
	v_mul_f32_e32 v53, 0x45800000, v52
	v_cndmask_b32_e32 v52, v52, v53, vcc
	v_pk_mul_f32 v[46:47], v[52:53], v[46:47] op_sel_hi:[0,1]
	v_pk_mul_f32 v[46:47], v[2:3], v[46:47]
	v_pk_mul_f32 v[50:51], v[52:53], v[50:51] op_sel_hi:[0,1]
	v_pk_mul_f32 v[46:47], v[46:47], v[56:57]
	v_pk_mul_f32 v[50:51], v[0:1], v[50:51]
	v_cvt_pk_bf16_f32 v43, v46, v47
	v_lshlrev_b32_e32 v46, 16, v42
	v_and_b32_e32 v47, 0xffff0000, v42
	v_pk_mul_f32 v[46:47], v[50:51], v[46:47]
	v_pk_mul_f32 v[44:45], v[52:53], v[44:45] op_sel_hi:[0,1]
	v_cvt_pk_bf16_f32 v42, v46, v47
	v_lshlrev_b32_e32 v46, 16, v41
	v_and_b32_e32 v47, 0xffff0000, v41
	v_pk_mul_f32 v[44:45], v[6:7], v[44:45]
	v_lshl_add_u64 v[54:55], v[70:71], 0, s[22:23]
	v_pk_mul_f32 v[44:45], v[44:45], v[46:47]
	v_pk_mul_f32 v[46:47], v[52:53], v[48:49] op_sel_hi:[0,1]
	v_cvt_pk_bf16_f32 v41, v44, v45
	v_lshlrev_b32_e32 v44, 16, v40
	v_and_b32_e32 v45, 0xffff0000, v40
	v_pk_mul_f32 v[46:47], v[4:5], v[46:47]
	s_nop 0
	v_pk_mul_f32 v[44:45], v[46:47], v[44:45]
	s_nop 0
	v_cvt_pk_bf16_f32 v40, v44, v45
	global_store_dwordx4 v[54:55], v[40:43], off
.LBB0_186:
	s_waitcnt vmcnt(7)
	s_nop 0
	v_lshlrev_b32_e32 v40, 16, v36
	v_and_b32_e32 v41, 0xffff0000, v36
	v_lshlrev_b32_e32 v36, 16, v37
	v_and_b32_e32 v37, 0xffff0000, v37
	v_pk_mul_f32 v[44:45], v[40:41], v[40:41]
	v_pk_mul_f32 v[46:47], v[36:37], v[36:37]
	v_add_f32_e32 v44, v44, v45
	v_lshlrev_b32_e32 v42, 16, v38
	v_and_b32_e32 v43, 0xffff0000, v38
	v_add_f32_e32 v44, v46, v44
	v_pk_mul_f32 v[48:49], v[42:43], v[42:43]
	v_add_f32_e32 v44, v47, v44
	v_lshlrev_b32_e32 v38, 16, v39
	v_and_b32_e32 v39, 0xffff0000, v39
	v_add_f32_e32 v44, v48, v44
	v_pk_mul_f32 v[50:51], v[38:39], v[38:39]
	v_add_f32_e32 v44, v49, v44
	v_add_f32_e32 v44, v50, v44
	v_add_f32_e32 v44, v51, v44
	s_andn2_b64 vcc, exec, s[20:21]
	v_mov_b32_e32 v45, v44
	s_nop 1
	v_permlane32_swap_b32_e32 v45, v44
	v_add_f32_e32 v44, v44, v45
	v_mov_b32_e32 v45, v44
	s_nop 1
	v_permlane16_swap_b32_e32 v45, v44
	v_add_f32_e32 v44, v44, v45
	s_nop 1
	v_add_f32_dpp v44, v44, v44 row_mirror row_mask:0xf bank_mask:0xf
	s_nop 1
	v_add_f32_dpp v44, v44, v44 row_half_mirror row_mask:0xf bank_mask:0xf
	s_nop 1
	v_add_f32_dpp v44, v44, v44 quad_perm:[2,3,0,1] row_mask:0xf bank_mask:0xf
	ds_bpermute_b32 v45, v79, v44
	s_cbranch_vccnz .LBB0_188
	s_waitcnt lgkmcnt(0)
	v_add_f32_e32 v44, v44, v45
	v_fmamk_f32 v44, v44, 0x3b000000, v188
	v_cmp_gt_f32_e32 vcc, s80, v44
	v_mul_f32_e32 v45, 0x4b800000, v44
	v_lshlrev_b32_e32 v48, 16, v35
	v_cndmask_b32_e32 v44, v44, v45, vcc
	v_rsq_f32_e32 v44, v44
	v_and_b32_e32 v49, 0xffff0000, v35
	s_ashr_i32 s19, s18, 31
	s_lshl_b64 s[18:19], s[18:19], 12
	v_mul_f32_e32 v45, 0x45800000, v44
	v_cndmask_b32_e32 v44, v44, v45, vcc
	v_pk_mul_f32 v[38:39], v[44:45], v[38:39] op_sel_hi:[0,1]
	v_pk_mul_f32 v[38:39], v[2:3], v[38:39]
	v_pk_mul_f32 v[42:43], v[44:45], v[42:43] op_sel_hi:[0,1]
	v_pk_mul_f32 v[38:39], v[38:39], v[48:49]
	v_pk_mul_f32 v[42:43], v[0:1], v[42:43]
	v_cvt_pk_bf16_f32 v35, v38, v39
	v_lshlrev_b32_e32 v38, 16, v34
	v_and_b32_e32 v39, 0xffff0000, v34
	v_pk_mul_f32 v[38:39], v[42:43], v[38:39]
	v_pk_mul_f32 v[36:37], v[44:45], v[36:37] op_sel_hi:[0,1]
	v_cvt_pk_bf16_f32 v34, v38, v39
	v_lshlrev_b32_e32 v38, 16, v33
	v_and_b32_e32 v39, 0xffff0000, v33
	v_pk_mul_f32 v[36:37], v[6:7], v[36:37]
	v_lshl_add_u64 v[46:47], v[70:71], 0, s[18:19]
	v_pk_mul_f32 v[36:37], v[36:37], v[38:39]
	v_pk_mul_f32 v[38:39], v[44:45], v[40:41] op_sel_hi:[0,1]
	v_cvt_pk_bf16_f32 v33, v36, v37
	v_lshlrev_b32_e32 v36, 16, v32
	v_and_b32_e32 v37, 0xffff0000, v32
	v_pk_mul_f32 v[38:39], v[4:5], v[38:39]
	s_nop 0
	v_pk_mul_f32 v[36:37], v[38:39], v[36:37]
	s_nop 0
	v_cvt_pk_bf16_f32 v32, v36, v37
	global_store_dwordx4 v[46:47], v[32:35], off
.LBB0_188:
	s_waitcnt vmcnt(5)
	s_nop 0
	v_lshlrev_b32_e32 v32, 16, v28
	v_and_b32_e32 v33, 0xffff0000, v28
	v_lshlrev_b32_e32 v28, 16, v29
	v_and_b32_e32 v29, 0xffff0000, v29
	v_pk_mul_f32 v[36:37], v[32:33], v[32:33]
	v_pk_mul_f32 v[38:39], v[28:29], v[28:29]
	v_add_f32_e32 v36, v36, v37
	v_lshlrev_b32_e32 v34, 16, v30
	v_and_b32_e32 v35, 0xffff0000, v30
	v_add_f32_e32 v36, v38, v36
	v_pk_mul_f32 v[40:41], v[34:35], v[34:35]
	v_add_f32_e32 v36, v39, v36
	v_lshlrev_b32_e32 v30, 16, v31
	v_and_b32_e32 v31, 0xffff0000, v31
	v_add_f32_e32 v36, v40, v36
	v_pk_mul_f32 v[42:43], v[30:31], v[30:31]
	v_add_f32_e32 v36, v41, v36
	v_add_f32_e32 v36, v42, v36
	v_add_f32_e32 v36, v43, v36
	s_andn2_b64 vcc, exec, s[16:17]
	v_mov_b32_e32 v37, v36
	s_nop 1
	v_permlane32_swap_b32_e32 v37, v36
	v_add_f32_e32 v36, v36, v37
	v_mov_b32_e32 v37, v36
	s_nop 1
	v_permlane16_swap_b32_e32 v37, v36
	v_add_f32_e32 v36, v36, v37
	s_nop 1
	v_add_f32_dpp v36, v36, v36 row_mirror row_mask:0xf bank_mask:0xf
	s_nop 1
	v_add_f32_dpp v36, v36, v36 row_half_mirror row_mask:0xf bank_mask:0xf
	s_nop 1
	v_add_f32_dpp v36, v36, v36 quad_perm:[2,3,0,1] row_mask:0xf bank_mask:0xf
	ds_bpermute_b32 v37, v79, v36
	s_cbranch_vccnz .LBB0_190
	s_waitcnt lgkmcnt(0)
	v_add_f32_e32 v36, v36, v37
	v_fmamk_f32 v36, v36, 0x3b000000, v188
	v_cmp_gt_f32_e32 vcc, s80, v36
	v_mul_f32_e32 v37, 0x4b800000, v36
	v_lshlrev_b32_e32 v40, 16, v27
	v_cndmask_b32_e32 v36, v36, v37, vcc
	v_rsq_f32_e32 v36, v36
	v_and_b32_e32 v41, 0xffff0000, v27
	s_ashr_i32 s15, s14, 31
	s_lshl_b64 s[14:15], s[14:15], 12
	v_mul_f32_e32 v37, 0x45800000, v36
	v_cndmask_b32_e32 v36, v36, v37, vcc
	v_pk_mul_f32 v[30:31], v[36:37], v[30:31] op_sel_hi:[0,1]
	v_pk_mul_f32 v[30:31], v[2:3], v[30:31]
	v_pk_mul_f32 v[34:35], v[36:37], v[34:35] op_sel_hi:[0,1]
	v_pk_mul_f32 v[30:31], v[30:31], v[40:41]
	v_pk_mul_f32 v[34:35], v[0:1], v[34:35]
	v_cvt_pk_bf16_f32 v27, v30, v31
	v_lshlrev_b32_e32 v30, 16, v26
	v_and_b32_e32 v31, 0xffff0000, v26
	v_pk_mul_f32 v[30:31], v[34:35], v[30:31]
	v_pk_mul_f32 v[28:29], v[36:37], v[28:29] op_sel_hi:[0,1]
	v_cvt_pk_bf16_f32 v26, v30, v31
	v_lshlrev_b32_e32 v30, 16, v25
	v_and_b32_e32 v31, 0xffff0000, v25
	v_pk_mul_f32 v[28:29], v[6:7], v[28:29]
	v_lshl_add_u64 v[38:39], v[70:71], 0, s[14:15]
	v_pk_mul_f32 v[28:29], v[28:29], v[30:31]
	v_pk_mul_f32 v[30:31], v[36:37], v[32:33] op_sel_hi:[0,1]
	v_cvt_pk_bf16_f32 v25, v28, v29
	v_lshlrev_b32_e32 v28, 16, v24
	v_and_b32_e32 v29, 0xffff0000, v24
	v_pk_mul_f32 v[30:31], v[4:5], v[30:31]
	s_nop 0
	v_pk_mul_f32 v[28:29], v[30:31], v[28:29]
	s_nop 0
	v_cvt_pk_bf16_f32 v24, v28, v29
	global_store_dwordx4 v[38:39], v[24:27], off
.LBB0_190:
	s_waitcnt vmcnt(3)
	s_nop 0
	v_lshlrev_b32_e32 v24, 16, v20
	v_and_b32_e32 v25, 0xffff0000, v20
	v_lshlrev_b32_e32 v20, 16, v21
	v_and_b32_e32 v21, 0xffff0000, v21
	v_pk_mul_f32 v[28:29], v[24:25], v[24:25]
	v_pk_mul_f32 v[30:31], v[20:21], v[20:21]
	v_add_f32_e32 v28, v28, v29
	v_lshlrev_b32_e32 v26, 16, v22
	v_and_b32_e32 v27, 0xffff0000, v22
	v_add_f32_e32 v28, v30, v28
	v_pk_mul_f32 v[32:33], v[26:27], v[26:27]
	v_add_f32_e32 v28, v31, v28
	v_lshlrev_b32_e32 v22, 16, v23
	v_and_b32_e32 v23, 0xffff0000, v23
	v_add_f32_e32 v28, v32, v28
	v_pk_mul_f32 v[34:35], v[22:23], v[22:23]
	v_add_f32_e32 v28, v33, v28
	v_add_f32_e32 v28, v34, v28
	v_add_f32_e32 v28, v35, v28
	s_andn2_b64 vcc, exec, s[12:13]
	v_mov_b32_e32 v29, v28
	s_nop 1
	v_permlane32_swap_b32_e32 v29, v28
	v_add_f32_e32 v28, v28, v29
	v_mov_b32_e32 v29, v28
	s_nop 1
	v_permlane16_swap_b32_e32 v29, v28
	v_add_f32_e32 v28, v28, v29
	s_nop 1
	v_add_f32_dpp v28, v28, v28 row_mirror row_mask:0xf bank_mask:0xf
	s_nop 1
	v_add_f32_dpp v28, v28, v28 row_half_mirror row_mask:0xf bank_mask:0xf
	s_nop 1
	v_add_f32_dpp v28, v28, v28 quad_perm:[2,3,0,1] row_mask:0xf bank_mask:0xf
	ds_bpermute_b32 v29, v79, v28
	s_cbranch_vccnz .LBB0_192
	s_waitcnt lgkmcnt(0)
	v_add_f32_e32 v28, v28, v29
	v_fmamk_f32 v28, v28, 0x3b000000, v188
	v_cmp_gt_f32_e32 vcc, s80, v28
	v_mul_f32_e32 v29, 0x4b800000, v28
	v_lshlrev_b32_e32 v32, 16, v19
	v_cndmask_b32_e32 v28, v28, v29, vcc
	v_rsq_f32_e32 v28, v28
	v_and_b32_e32 v33, 0xffff0000, v19
	s_ashr_i32 s11, s10, 31
	s_lshl_b64 s[10:11], s[10:11], 12
	v_mul_f32_e32 v29, 0x45800000, v28
	v_cndmask_b32_e32 v28, v28, v29, vcc
	v_pk_mul_f32 v[22:23], v[28:29], v[22:23] op_sel_hi:[0,1]
	v_pk_mul_f32 v[22:23], v[2:3], v[22:23]
	v_pk_mul_f32 v[26:27], v[28:29], v[26:27] op_sel_hi:[0,1]
	v_pk_mul_f32 v[22:23], v[22:23], v[32:33]
	v_pk_mul_f32 v[26:27], v[0:1], v[26:27]
	v_cvt_pk_bf16_f32 v19, v22, v23
	v_lshlrev_b32_e32 v22, 16, v18
	v_and_b32_e32 v23, 0xffff0000, v18
	v_pk_mul_f32 v[22:23], v[26:27], v[22:23]
	v_pk_mul_f32 v[20:21], v[28:29], v[20:21] op_sel_hi:[0,1]
	v_cvt_pk_bf16_f32 v18, v22, v23
	v_lshlrev_b32_e32 v22, 16, v17
	v_and_b32_e32 v23, 0xffff0000, v17
	v_pk_mul_f32 v[20:21], v[6:7], v[20:21]
	v_lshl_add_u64 v[30:31], v[70:71], 0, s[10:11]
	v_pk_mul_f32 v[20:21], v[20:21], v[22:23]
	v_pk_mul_f32 v[22:23], v[28:29], v[24:25] op_sel_hi:[0,1]
	v_cvt_pk_bf16_f32 v17, v20, v21
	v_lshlrev_b32_e32 v20, 16, v16
	v_and_b32_e32 v21, 0xffff0000, v16
	v_pk_mul_f32 v[22:23], v[4:5], v[22:23]
	s_nop 0
	v_pk_mul_f32 v[20:21], v[22:23], v[20:21]
	s_nop 0
	v_cvt_pk_bf16_f32 v16, v20, v21
	global_store_dwordx4 v[30:31], v[16:19], off
.LBB0_192:
	s_waitcnt vmcnt(2)
	s_nop 0
	v_lshlrev_b32_e32 v16, 16, v12
	v_and_b32_e32 v17, 0xffff0000, v12
	v_lshlrev_b32_e32 v12, 16, v13
	v_and_b32_e32 v13, 0xffff0000, v13
	v_pk_mul_f32 v[20:21], v[16:17], v[16:17]
	v_pk_mul_f32 v[22:23], v[12:13], v[12:13]
	v_add_f32_e32 v20, v20, v21
	v_lshlrev_b32_e32 v18, 16, v14
	v_and_b32_e32 v19, 0xffff0000, v14
	v_add_f32_e32 v20, v22, v20
	v_pk_mul_f32 v[24:25], v[18:19], v[18:19]
	v_add_f32_e32 v20, v23, v20
	v_lshlrev_b32_e32 v14, 16, v15
	v_and_b32_e32 v15, 0xffff0000, v15
	v_add_f32_e32 v20, v24, v20
	v_pk_mul_f32 v[26:27], v[14:15], v[14:15]
	v_add_f32_e32 v20, v25, v20
	v_add_f32_e32 v20, v26, v20
	v_add_f32_e32 v20, v27, v20
	s_andn2_b64 vcc, exec, s[8:9]
	v_mov_b32_e32 v21, v20
	s_nop 1
	v_permlane32_swap_b32_e32 v21, v20
	v_add_f32_e32 v20, v20, v21
	v_mov_b32_e32 v21, v20
	s_nop 1
	v_permlane16_swap_b32_e32 v21, v20
	v_add_f32_e32 v20, v20, v21
	s_nop 1
	v_add_f32_dpp v20, v20, v20 row_mirror row_mask:0xf bank_mask:0xf
	s_nop 1
	v_add_f32_dpp v20, v20, v20 row_half_mirror row_mask:0xf bank_mask:0xf
	s_nop 1
	v_add_f32_dpp v20, v20, v20 quad_perm:[2,3,0,1] row_mask:0xf bank_mask:0xf
	ds_bpermute_b32 v21, v79, v20
	s_cbranch_vccnz .LBB0_179
	s_waitcnt lgkmcnt(0)
	v_add_f32_e32 v20, v20, v21
	v_fmamk_f32 v20, v20, 0x3b000000, v188
	v_cmp_gt_f32_e32 vcc, s80, v20
	v_mul_f32_e32 v21, 0x4b800000, v20
	s_waitcnt vmcnt(1)
	v_lshlrev_b32_e32 v24, 16, v11
	v_cndmask_b32_e32 v20, v20, v21, vcc
	v_rsq_f32_e32 v20, v20
	v_and_b32_e32 v25, 0xffff0000, v11
	s_ashr_i32 s7, s6, 31
	s_lshl_b64 s[6:7], s[6:7], 12
	v_mul_f32_e32 v21, 0x45800000, v20
	v_cndmask_b32_e32 v20, v20, v21, vcc
	v_pk_mul_f32 v[14:15], v[20:21], v[14:15] op_sel_hi:[0,1]
	v_pk_mul_f32 v[14:15], v[2:3], v[14:15]
	v_pk_mul_f32 v[18:19], v[20:21], v[18:19] op_sel_hi:[0,1]
	v_pk_mul_f32 v[14:15], v[14:15], v[24:25]
	v_pk_mul_f32 v[18:19], v[0:1], v[18:19]
	v_cvt_pk_bf16_f32 v11, v14, v15
	v_lshlrev_b32_e32 v14, 16, v10
	v_and_b32_e32 v15, 0xffff0000, v10
	v_pk_mul_f32 v[14:15], v[18:19], v[14:15]
	v_pk_mul_f32 v[12:13], v[20:21], v[12:13] op_sel_hi:[0,1]
	v_cvt_pk_bf16_f32 v10, v14, v15
	v_lshlrev_b32_e32 v14, 16, v9
	v_and_b32_e32 v15, 0xffff0000, v9
	v_pk_mul_f32 v[12:13], v[6:7], v[12:13]
	v_lshl_add_u64 v[22:23], v[70:71], 0, s[6:7]
	v_pk_mul_f32 v[12:13], v[12:13], v[14:15]
	v_pk_mul_f32 v[14:15], v[20:21], v[16:17] op_sel_hi:[0,1]
	v_cvt_pk_bf16_f32 v9, v12, v13
	v_lshlrev_b32_e32 v12, 16, v8
	v_and_b32_e32 v13, 0xffff0000, v8
	v_pk_mul_f32 v[14:15], v[4:5], v[14:15]
	s_nop 0
	v_pk_mul_f32 v[12:13], v[14:15], v[12:13]
	s_nop 0
	v_cvt_pk_bf16_f32 v8, v12, v13
	global_store_dwordx4 v[22:23], v[8:11], off
	s_branch .LBB0_179

.LBB0_258:
	s_andn2_b64 vcc, exec, s[0:1]
	s_cbranch_vccnz .LBB0_261
	s_cmpk_gt_u32 s39, 0xb7f
	s_cbranch_scc1 .LBB0_261
	v_add_u32_e32 v0, s38, v89
	v_add_u32_e32 v86, 0xffffe200, v0
	v_add_u32_e32 v80, 0xfffff200, v0
	v_ashrrev_i32_e32 v87, 31, v86
	v_lshlrev_b64 v[0:1], 13, v[86:87]
	v_ashrrev_i32_e32 v81, 31, v80
	v_lshl_add_u64 v[0:1], v[68:69], 0, v[0:1]
	v_lshlrev_b64 v[2:3], 13, v[80:81]
	v_lshl_add_u64 v[2:3], v[68:69], 0, v[2:3]
	global_load_dwordx4 v[104:107], v[70:71], off
	global_load_dwordx4 v[108:111], v[70:71], off offset:1024
	global_load_dwordx4 v[112:115], v[70:71], off offset:2048
	global_load_dwordx4 v[116:119], v[70:71], off offset:3072
	global_load_dwordx4 v[120:123], v[72:73], off
	global_load_dwordx4 v[124:127], v[74:75], off
	global_load_dwordx4 v[128:131], v[76:77], off
	global_load_dwordx4 v[132:135], v[78:79], off
	global_load_dwordx4 v[60:63], v[0:1], off nt
	global_load_dwordx4 v[56:59], v[2:3], off nt
	global_load_dwordx4 v[52:55], v[0:1], off offset:1024 nt
	global_load_dwordx4 v[48:51], v[2:3], off offset:1024 nt
	global_load_dwordx4 v[44:47], v[0:1], off offset:2048 nt
	global_load_dwordx4 v[40:43], v[2:3], off offset:2048 nt
	global_load_dwordx4 v[36:39], v[0:1], off offset:3072 nt
	global_load_dwordx4 v[32:35], v[2:3], off offset:3072 nt
	v_add_co_u32_e32 v0, vcc, s29, v0
	v_lshlrev_b64 v[86:87], 12, v[86:87]
	s_nop 0
	v_addc_co_u32_e32 v1, vcc, 0, v1, vcc
	global_load_dwordx4 v[28:31], v[0:1], off nt
	v_add_co_u32_e32 v2, vcc, s29, v2
	v_lshlrev_b64 v[80:81], 12, v[80:81]
	s_nop 0
	v_addc_co_u32_e32 v3, vcc, 0, v3, vcc
	global_load_dwordx4 v[24:27], v[2:3], off nt
	global_load_dwordx4 v[20:23], v[0:1], off offset:1024 nt
	global_load_dwordx4 v[16:19], v[2:3], off offset:1024 nt
	global_load_dwordx4 v[12:15], v[0:1], off offset:2048 nt
	global_load_dwordx4 v[8:11], v[2:3], off offset:2048 nt
	global_load_dwordx4 v[4:7], v[0:1], off offset:3072 nt
	s_nop 0
	global_load_dwordx4 v[0:3], v[2:3], off offset:3072 nt
	v_cmp_lt_i32_e32 vcc, v228, v227
	v_lshl_add_u64 v[86:87], v[66:67], 0, v[86:87]
	v_lshl_add_u64 v[80:81], v[66:67], 0, v[80:81]
	s_waitcnt vmcnt(15)
	v_mov_b32_e32 v95, v61
	s_waitcnt vmcnt(14)
	v_mov_b32_e32 v94, v57
	v_pk_mul_f32 v[94:95], v[94:95], v[94:95]
	s_waitcnt vmcnt(12)
	v_mov_b32_e32 v96, v49
	v_mov_b32_e32 v97, v53
	v_pk_mul_f32 v[96:97], v[96:97], v[96:97]
	s_waitcnt vmcnt(7)
	v_mov_b32_e32 v84, v29
	s_waitcnt vmcnt(5)
	v_mov_b32_e32 v85, v21
	v_mov_b32_e32 v82, v28
	v_mov_b32_e32 v83, v20
	v_pk_mul_f32 v[84:85], v[84:85], v[84:85]
	v_mov_b32_e32 v92, v25
	v_pk_fma_f32 v[82:83], v[82:83], v[82:83], v[84:85]
	v_mov_b32_e32 v84, v30
	v_mov_b32_e32 v85, v22
	v_pk_fma_f32 v[82:83], v[84:85], v[84:85], v[82:83]
	v_mov_b32_e32 v84, v31
	v_mov_b32_e32 v85, v23
	s_waitcnt vmcnt(4)
	v_mov_b32_e32 v93, v17
	v_pk_fma_f32 v[82:83], v[84:85], v[84:85], v[82:83]
	v_mov_b32_e32 v84, v24
	v_mov_b32_e32 v85, v16
	v_pk_mul_f32 v[92:93], v[92:93], v[92:93]
	s_waitcnt vmcnt(2)
	v_mov_b32_e32 v98, v9
	v_pk_fma_f32 v[84:85], v[84:85], v[84:85], v[92:93]
	v_mov_b32_e32 v92, v26
	v_mov_b32_e32 v93, v18
	v_pk_fma_f32 v[84:85], v[92:93], v[92:93], v[84:85]
	v_mov_b32_e32 v92, v27
	v_mov_b32_e32 v93, v19
	v_pk_fma_f32 v[84:85], v[92:93], v[92:93], v[84:85]
	v_mov_b32_e32 v92, v56
	v_mov_b32_e32 v93, v60
	v_pk_fma_f32 v[92:93], v[92:93], v[92:93], v[94:95]
	v_mov_b32_e32 v94, v58
	v_mov_b32_e32 v95, v62
	v_pk_fma_f32 v[92:93], v[94:95], v[94:95], v[92:93]
	v_mov_b32_e32 v94, v59
	v_mov_b32_e32 v95, v63
	v_pk_fma_f32 v[92:93], v[94:95], v[94:95], v[92:93]
	v_mov_b32_e32 v94, v48
	v_mov_b32_e32 v95, v52
	v_pk_fma_f32 v[94:95], v[94:95], v[94:95], v[96:97]
	v_mov_b32_e32 v96, v50
	v_mov_b32_e32 v97, v54
	v_pk_fma_f32 v[94:95], v[96:97], v[96:97], v[94:95]
	v_mov_b32_e32 v96, v51
	v_mov_b32_e32 v97, v55
	v_pk_fma_f32 v[94:95], v[96:97], v[96:97], v[94:95]
	v_mov_b32_e32 v96, v41
	v_mov_b32_e32 v97, v45
	v_pk_add_f32 v[92:93], v[92:93], v[94:95]
	v_mov_b32_e32 v94, v40
	v_mov_b32_e32 v95, v44
	v_pk_mul_f32 v[96:97], v[96:97], v[96:97]
	s_waitcnt vmcnt(0)
	v_mov_b32_e32 v99, v1
	v_pk_fma_f32 v[94:95], v[94:95], v[94:95], v[96:97]
	v_mov_b32_e32 v96, v42
	v_mov_b32_e32 v97, v46
	v_pk_fma_f32 v[94:95], v[96:97], v[96:97], v[94:95]
	v_mov_b32_e32 v96, v43
	v_mov_b32_e32 v97, v47
	v_pk_fma_f32 v[94:95], v[96:97], v[96:97], v[94:95]
	v_mov_b32_e32 v96, v33
	v_mov_b32_e32 v97, v37
	v_pk_add_f32 v[92:93], v[92:93], v[94:95]
	v_mov_b32_e32 v94, v32
	v_mov_b32_e32 v95, v36
	v_pk_mul_f32 v[96:97], v[96:97], v[96:97]
	v_pk_mul_f32 v[98:99], v[98:99], v[98:99]
	v_pk_fma_f32 v[94:95], v[94:95], v[94:95], v[96:97]
	v_mov_b32_e32 v96, v34
	v_mov_b32_e32 v97, v38
	v_pk_fma_f32 v[94:95], v[96:97], v[96:97], v[94:95]
	v_mov_b32_e32 v96, v35
	v_mov_b32_e32 v97, v39
	v_pk_fma_f32 v[94:95], v[96:97], v[96:97], v[94:95]
	v_mov_b32_e32 v96, v13
	v_pk_add_f32 v[92:93], v[92:93], v[94:95]
	v_mov_b32_e32 v94, v84
	v_mov_b32_e32 v95, v82
	v_mov_b32_e32 v97, v5
	v_pk_add_f32 v[92:93], v[92:93], v[94:95]
	v_mov_b32_e32 v94, v12
	v_mov_b32_e32 v95, v4
	v_pk_mul_f32 v[96:97], v[96:97], v[96:97]
	v_cndmask_b32_e32 v82, v226, v228, vcc
	v_pk_fma_f32 v[94:95], v[94:95], v[94:95], v[96:97]
	v_mov_b32_e32 v96, v14
	v_mov_b32_e32 v97, v6
	v_pk_fma_f32 v[94:95], v[96:97], v[96:97], v[94:95]
	v_mov_b32_e32 v96, v15
	v_mov_b32_e32 v97, v7
	v_pk_fma_f32 v[94:95], v[96:97], v[96:97], v[94:95]
	v_mov_b32_e32 v96, v8
	v_mov_b32_e32 v97, v0
	v_pk_fma_f32 v[96:97], v[96:97], v[96:97], v[98:99]
	v_mov_b32_e32 v98, v10
	v_mov_b32_e32 v99, v2
	v_cmp_lt_i32_e32 vcc, v229, v227
	v_pk_fma_f32 v[96:97], v[98:99], v[98:99], v[96:97]
	v_mov_b32_e32 v98, v11
	v_mov_b32_e32 v99, v3
	v_lshlrev_b32_e32 v91, 2, v82
	v_cndmask_b32_e32 v82, v226, v229, vcc
	v_cmp_lt_i32_e32 vcc, v230, v227
	v_pk_fma_f32 v[96:97], v[98:99], v[98:99], v[96:97]
	v_lshlrev_b32_e32 v98, 2, v82
	v_cndmask_b32_e32 v82, v226, v230, vcc
	v_cmp_lt_i32_e32 vcc, v231, v227
	v_lshlrev_b32_e32 v99, 2, v82
	v_mov_b32_e32 v84, v96
	v_cndmask_b32_e32 v82, v226, v231, vcc
	v_cmp_lt_i32_e32 vcc, v232, v227
	v_lshlrev_b32_e32 v100, 2, v82
	s_nop 0
	v_cndmask_b32_e32 v82, v226, v232, vcc
	v_cmp_lt_i32_e32 vcc, v233, v227
	v_lshlrev_b32_e32 v101, 2, v82
	s_nop 0
	v_cndmask_b32_e32 v82, v226, v233, vcc
	v_lshlrev_b32_e32 v102, 2, v82
	v_mov_b32_e32 v82, v85
	v_pk_add_f32 v[82:83], v[92:93], v[82:83]
	v_mov_b32_e32 v85, v94
	v_pk_add_f32 v[82:83], v[82:83], v[84:85]
	v_mov_b32_e32 v94, v97
	v_pk_add_f32 v[82:83], v[82:83], v[94:95]
	v_mov_b32_e32 v85, v83
	v_mov_b32_e32 v84, v82
	s_nop 1
	v_permlane32_swap_b32_e32 v85, v83
	v_permlane32_swap_b32_e32 v84, v82
	v_add_f32_e32 v83, v83, v85
	v_add_f32_e32 v82, v82, v84
	v_mov_b32_e32 v85, v83
	v_mov_b32_e32 v84, v82
	s_nop 1
	v_permlane16_swap_b32_e32 v85, v83
	v_permlane16_swap_b32_e32 v84, v82
	v_add_f32_e32 v83, v83, v85
	v_add_f32_e32 v82, v82, v84
	s_nop 1
	v_add_f32_dpp v82, v82, v82 row_mirror row_mask:0xf bank_mask:0xf
	v_add_f32_dpp v83, v83, v83 row_mirror row_mask:0xf bank_mask:0xf
	s_nop 1
	v_add_f32_dpp v82, v82, v82 row_half_mirror row_mask:0xf bank_mask:0xf
	v_add_f32_dpp v83, v83, v83 row_half_mirror row_mask:0xf bank_mask:0xf
	s_nop 1
	v_add_f32_dpp v82, v82, v82 quad_perm:[2,3,0,1] row_mask:0xf bank_mask:0xf
	v_add_f32_dpp v83, v83, v83 quad_perm:[2,3,0,1] row_mask:0xf bank_mask:0xf
	s_nop 1
	v_add_f32_dpp v82, v82, v82 quad_perm:[1,0,3,2] row_mask:0xf bank_mask:0xf
	v_add_f32_dpp v83, v83, v83 quad_perm:[1,0,3,2] row_mask:0xf bank_mask:0xf
	s_nop 0
	v_pk_fma_f32 v[82:83], v[82:83], s[34:35], v[188:189] op_sel_hi:[1,0,0]
	s_nop 0
	v_mul_f32_e32 v84, 0x4b800000, v83
	v_cmp_gt_f32_e64 s[10:11], s80, v83
	v_cmp_gt_f32_e32 vcc, s80, v82
	s_nop 0
	v_cndmask_b32_e64 v83, v83, v84, s[10:11]
	v_rsq_f32_e32 v83, v83
	s_nop 0
	v_mul_f32_e32 v84, 0x45800000, v83
	v_cndmask_b32_e64 v84, v83, v84, s[10:11]
	v_mul_f32_e32 v83, 0x4b800000, v82
	v_cndmask_b32_e32 v82, v82, v83, vcc
	v_rsq_f32_e32 v82, v82
	v_pk_mul_f32 v[60:61], v[60:61], v[84:85] op_sel_hi:[1,0]
	v_pk_mul_f32 v[62:63], v[62:63], v[84:85] op_sel_hi:[1,0]
	v_pk_mul_f32 v[52:53], v[52:53], v[84:85] op_sel_hi:[1,0]
	v_mul_f32_e32 v83, 0x45800000, v82
	v_cndmask_b32_e32 v82, v82, v83, vcc
	v_pk_mul_f32 v[56:57], v[56:57], v[82:83] op_sel_hi:[1,0]
	v_pk_mul_f32 v[58:59], v[58:59], v[82:83] op_sel_hi:[1,0]
	v_pk_mul_f32 v[54:55], v[54:55], v[84:85] op_sel_hi:[1,0]
	v_pk_mul_f32 v[48:49], v[48:49], v[82:83] op_sel_hi:[1,0]
	v_pk_mul_f32 v[50:51], v[50:51], v[82:83] op_sel_hi:[1,0]
	v_pk_mul_f32 v[44:45], v[44:45], v[84:85] op_sel_hi:[1,0]
	v_pk_mul_f32 v[46:47], v[46:47], v[84:85] op_sel_hi:[1,0]
	v_pk_mul_f32 v[40:41], v[40:41], v[82:83] op_sel_hi:[1,0]
	v_pk_mul_f32 v[42:43], v[42:43], v[82:83] op_sel_hi:[1,0]
	v_pk_mul_f32 v[36:37], v[36:37], v[84:85] op_sel_hi:[1,0]
	v_pk_mul_f32 v[38:39], v[38:39], v[84:85] op_sel_hi:[1,0]
	v_pk_mul_f32 v[32:33], v[32:33], v[82:83] op_sel_hi:[1,0]
	v_pk_mul_f32 v[34:35], v[34:35], v[82:83] op_sel_hi:[1,0]
	v_pk_mul_f32 v[28:29], v[28:29], v[84:85] op_sel_hi:[1,0]
	v_pk_mul_f32 v[30:31], v[30:31], v[84:85] op_sel_hi:[1,0]
	v_pk_mul_f32 v[24:25], v[24:25], v[82:83] op_sel_hi:[1,0]
	s_waitcnt vmcnt(0)
	v_pk_mul_f32 v[60:61], v[104:105], v[60:61]
	v_pk_mul_f32 v[62:63], v[106:107], v[62:63]
	v_pk_mul_f32 v[56:57], v[104:105], v[56:57]
	v_pk_mul_f32 v[58:59], v[106:107], v[58:59]
	v_cvt_pk_bf16_f32 v60, v60, v61
	v_cvt_pk_bf16_f32 v61, v62, v63
	v_cvt_pk_bf16_f32 v56, v56, v57
	v_cvt_pk_bf16_f32 v57, v58, v59
	global_store_dwordx2 v[86:87], v[60:61], off
	global_store_dwordx2 v[80:81], v[56:57], off
	v_pk_mul_f32 v[26:27], v[26:27], v[82:83] op_sel_hi:[1,0]
	v_pk_mul_f32 v[20:21], v[20:21], v[84:85] op_sel_hi:[1,0]
	v_pk_mul_f32 v[22:23], v[22:23], v[84:85] op_sel_hi:[1,0]
	v_pk_mul_f32 v[16:17], v[16:17], v[82:83] op_sel_hi:[1,0]
	v_pk_mul_f32 v[18:19], v[18:19], v[82:83] op_sel_hi:[1,0]
	v_pk_mul_f32 v[12:13], v[12:13], v[84:85] op_sel_hi:[1,0]
	v_pk_mul_f32 v[14:15], v[14:15], v[84:85] op_sel_hi:[1,0]
	v_pk_mul_f32 v[8:9], v[8:9], v[82:83] op_sel_hi:[1,0]
	v_pk_mul_f32 v[10:11], v[10:11], v[82:83] op_sel_hi:[1,0]
	v_pk_mul_f32 v[4:5], v[4:5], v[84:85] op_sel_hi:[1,0]
	v_pk_mul_f32 v[6:7], v[6:7], v[84:85] op_sel_hi:[1,0]
	v_pk_mul_f32 v[0:1], v[0:1], v[82:83] op_sel_hi:[1,0]
	v_pk_mul_f32 v[2:3], v[2:3], v[82:83] op_sel_hi:[1,0]
	v_pk_mul_f32 v[52:53], v[52:53], v[108:109]
	v_pk_mul_f32 v[54:55], v[54:55], v[110:111]
	v_pk_mul_f32 v[48:49], v[108:109], v[48:49]
	v_pk_mul_f32 v[50:51], v[50:51], v[110:111]
	v_cvt_pk_bf16_f32 v52, v52, v53
	v_cvt_pk_bf16_f32 v53, v54, v55
	v_cvt_pk_bf16_f32 v48, v48, v49
	v_cvt_pk_bf16_f32 v49, v50, v51
	global_store_dwordx2 v[86:87], v[52:53], off offset:512
	global_store_dwordx2 v[80:81], v[48:49], off offset:512
	v_pk_mul_f32 v[44:45], v[44:45], v[112:113]
	v_pk_mul_f32 v[46:47], v[46:47], v[114:115]
	v_pk_mul_f32 v[40:41], v[40:41], v[112:113]
	v_pk_mul_f32 v[42:43], v[42:43], v[114:115]
	v_cvt_pk_bf16_f32 v44, v44, v45
	v_cvt_pk_bf16_f32 v45, v46, v47
	v_cvt_pk_bf16_f32 v40, v40, v41
	v_cvt_pk_bf16_f32 v41, v42, v43
	global_store_dwordx2 v[86:87], v[44:45], off offset:1024
	global_store_dwordx2 v[80:81], v[40:41], off offset:1024
	v_pk_mul_f32 v[36:37], v[36:37], v[116:117]
	v_pk_mul_f32 v[38:39], v[38:39], v[118:119]
	v_pk_mul_f32 v[32:33], v[32:33], v[116:117]
	v_pk_mul_f32 v[34:35], v[34:35], v[118:119]
	v_cvt_pk_bf16_f32 v36, v36, v37
	v_cvt_pk_bf16_f32 v37, v38, v39
	v_cvt_pk_bf16_f32 v32, v32, v33
	v_cvt_pk_bf16_f32 v33, v34, v35
	global_store_dwordx2 v[86:87], v[36:37], off offset:1536
	global_store_dwordx2 v[80:81], v[32:33], off offset:1536
	v_pk_mul_f32 v[28:29], v[28:29], v[120:121]
	v_pk_mul_f32 v[30:31], v[30:31], v[122:123]
	v_pk_mul_f32 v[24:25], v[24:25], v[120:121]
	v_pk_mul_f32 v[26:27], v[26:27], v[122:123]
	v_cvt_pk_bf16_f32 v28, v28, v29
	v_cvt_pk_bf16_f32 v29, v30, v31
	v_cvt_pk_bf16_f32 v24, v24, v25
	v_cvt_pk_bf16_f32 v25, v26, v27
	global_store_dwordx2 v[86:87], v[28:29], off offset:2048
	global_store_dwordx2 v[80:81], v[24:25], off offset:2048
	v_pk_mul_f32 v[20:21], v[20:21], v[124:125]
	v_pk_mul_f32 v[22:23], v[22:23], v[126:127]
	v_pk_mul_f32 v[16:17], v[16:17], v[124:125]
	v_pk_mul_f32 v[18:19], v[18:19], v[126:127]
	v_cvt_pk_bf16_f32 v20, v20, v21
	v_cvt_pk_bf16_f32 v21, v22, v23
	v_cvt_pk_bf16_f32 v16, v16, v17
	v_cvt_pk_bf16_f32 v17, v18, v19
	global_store_dwordx2 v[86:87], v[20:21], off offset:2560
	global_store_dwordx2 v[80:81], v[16:17], off offset:2560
	v_pk_mul_f32 v[12:13], v[12:13], v[128:129]
	v_pk_mul_f32 v[14:15], v[14:15], v[130:131]
	v_pk_mul_f32 v[8:9], v[8:9], v[128:129]
	v_pk_mul_f32 v[10:11], v[10:11], v[130:131]
	v_cvt_pk_bf16_f32 v12, v12, v13
	v_cvt_pk_bf16_f32 v13, v14, v15
	v_cvt_pk_bf16_f32 v8, v8, v9
	v_cvt_pk_bf16_f32 v9, v10, v11
	global_store_dwordx2 v[86:87], v[12:13], off offset:3072
	global_store_dwordx2 v[80:81], v[8:9], off offset:3072
	v_pk_mul_f32 v[4:5], v[4:5], v[132:133]
	v_pk_mul_f32 v[6:7], v[6:7], v[134:135]
	v_pk_mul_f32 v[0:1], v[0:1], v[132:133]
	v_pk_mul_f32 v[2:3], v[2:3], v[134:135]
	v_cvt_pk_bf16_f32 v4, v4, v5
	v_cvt_pk_bf16_f32 v5, v6, v7
	v_cvt_pk_bf16_f32 v0, v0, v1
	v_cvt_pk_bf16_f32 v1, v2, v3
	global_store_dwordx2 v[86:87], v[4:5], off offset:3584
	global_store_dwordx2 v[80:81], v[0:1], off offset:3584
